# hand-written MoBA attention routine (f32-MFMA gates, tr-read V, pipelined LDS reads) replacing both inlined moba_task instances
# speedup vs baseline: 1.0285x; 1.0285x over previous
.Lmb_entry:
	s_lshr_b32 s1, s96, 5
	s_and_b32 s1, s1, 7
	s_and_b32 s4, s96, 7
	s_lshl_b32 s38, s4, 25
	s_mov_b32 s39, 0
	s_lshl_b32 s5, s4, 3
	s_add_u32 s5, s5, s1
	s_lshl_b32 s1, s1, 7
	s_bfe_u32 s6, s96, 0x20003
	v_mbcnt_lo_u32_b32 v165, -1, 0
	v_mbcnt_hi_u32_b32 v165, -1, v165
	v_mov_b32_e32 v167, 64
	v_xor_b32_e32 v199, 1, v165
	v_lshlrev_b32_e32 v199, 2, v199
	v_xor_b32_e32 v200, 2, v165
	v_lshlrev_b32_e32 v200, 2, v200
	v_xor_b32_e32 v201, 16, v165
	v_lshlrev_b32_e32 v201, 2, v201
	v_xor_b32_e32 v202, 32, v165
	v_lshlrev_b32_e32 v202, 2, v202
	s_mov_b32 s72, 0x40c00000
	s_mov_b32 s73, 0xc61c4000
	s_mov_b32 s74, 0xefa18f08
	s_mov_b32 s75, 0x3e0293ee
	v_mov_b32_e32 v134, 0xff61b1e6
	v_mov_b32_e32 v135, 0x7f61b1e6
	v_lshrrev_b32_e32 v139, 6, v198
	s_nop 0
	v_readfirstlane_b32 s7, v139
	s_lshl_b32 s25, s1, 1
	s_add_u32 s8, s66, s38
	s_addc_u32 s9, s67, 0
	s_add_u32 s8, s8, s25
	s_addc_u32 s9, s9, 0
	s_add_u32 s8, s8, 0x2000
	s_addc_u32 s9, s9, 0
	s_lshl_b32 s26, s4, 23
	s_add_u32 s10, s50, s26
	s_addc_u32 s11, s51, 0
	s_add_u32 s10, s10, s25
	s_addc_u32 s11, s11, 0
	s_add_u32 s10, s10, 0x800
	s_addc_u32 s11, s11, 0
	s_lshl_b32 s26, s5, 12
	s_add_u32 s12, s76, s26
	s_addc_u32 s13, s77, 0
	v_lshrrev_b32_e32 v139, 4, v198
	v_and_b32_e32 v140, 15, v198
	v_lshlrev_b32_e32 v140, 4, v140
	v_lshl_add_u32 v132, v139, 14, v140
	v_add_u32_e32 v133, 0x80000, v132
	s_movk_i32 s25, 272
	v_mad_u32_u24 v130, v139, s25, v140
	v_xor_b32_e32 v130, 65536, v130
	s_movk_i32 s25, 288
	v_mad_u32_u24 v131, v139, s25, v140
	v_add_u32_e32 v131, 82944, v131
	v_and_b32_e32 v139, 15, v165
	v_lshrrev_b32_e32 v140, 4, v165
	s_movk_i32 s25, 272
	v_lshlrev_b32_e32 v141, 4, v140
	v_mad_u32_u24 v128, v139, s25, v141
	v_lshrrev_b32_e32 v141, 2, v139
	v_lshl_add_u32 v141, v140, 2, v141
	v_and_b32_e32 v142, 3, v139
	v_lshlrev_b32_e32 v142, 3, v142
	s_movk_i32 s25, 288
	v_mad_u32_u24 v129, v141, s25, v142
	v_add_u32_e32 v129, 17408, v129
	s_lshl_b32 s25, s7, 5
	v_lshlrev_b32_e32 v141, 2, v140
	v_sub_u32_e32 v136, v139, v141
	v_add_u32_e32 v136, s25, v136
	s_mov_b32 s14, 0
.Lmb_task:
	s_sub_u32 s15, 7, s6
	s_cmp_eq_u32 s14, 0
	s_cselect_b32 s15, s15, s6
	s_lshl_b32 s16, s15, 2
	s_add_u32 s16, s16, 4
	s_lshl_b32 s25, s15, 22
	s_add_u32 s18, s8, s25
	s_addc_u32 s19, s9, 0
	s_mov_b32 s25, 0
	s_lshl_b32 s33, s15, 2
	s_add_u32 s33, s33, s25
	s_sub_u32 s26, s25, 4
	s_cmp_lt_u32 s25, 4
	s_cselect_b32 s26, s33, s26
	s_lshl_b32 s33, s26, 20
	s_add_u32 s20, s8, s33
	s_addc_u32 s21, s9, 0
	global_load_dwordx4 v[168:171], v132, s[20:21] offset:2048
	global_load_dwordx4 v[172:175], v133, s[20:21] offset:2048
	s_add_u32 s20, s20, 0x1000
	s_addc_u32 s21, s21, 0
	global_load_dwordx4 v[176:179], v132, s[20:21]
	global_load_dwordx4 v[180:183], v133, s[20:21]
	v_and_b32_e32 v139, 15, v165
	s_lshl_b32 s25, s7, 5
	v_add_u32_e32 v139, s25, v139
	v_lshlrev_b32_e32 v139, 14, v139
	v_lshrrev_b32_e32 v140, 4, v165
	s_cmp_lt_u32 s15, 4
	s_cbranch_scc1 .Lmb_sel_small
	v_lshl_add_u32 v141, v140, 6, v139
	v_and_b32_e32 v142, 7, v165
	v_lshlrev_b32_e32 v142, 9, v142
	v_lshl_add_u32 v142, v140, 7, v142
	global_load_dwordx4 v[0:3], v142, s[12:13] offset:0
	global_load_dwordx4 v[4:7], v142, s[12:13] offset:16
	global_load_dwordx4 v[8:11], v142, s[12:13] offset:32
	global_load_dwordx4 v[12:15], v142, s[12:13] offset:48
	global_load_dwordx4 v[16:19], v142, s[12:13] offset:64
	global_load_dwordx4 v[20:23], v142, s[12:13] offset:80
	global_load_dwordx4 v[24:27], v142, s[12:13] offset:96
	global_load_dwordx4 v[28:31], v142, s[12:13] offset:112
	s_add_u32 s22, s18, 0
	s_addc_u32 s23, s19, 0
	global_load_dwordx4 v[96:99], v141, s[22:23] offset:0
	global_load_dwordx4 v[100:103], v141, s[22:23] offset:16
	global_load_dwordx4 v[104:107], v141, s[22:23] offset:32
	global_load_dwordx4 v[108:111], v141, s[22:23] offset:48
	s_waitcnt vmcnt(0)
	v_lshlrev_b32_e32 v32, 16, v96
	v_and_b32_e32 v33, 0xffff0000, v96
	v_lshlrev_b32_e32 v34, 16, v97
	v_and_b32_e32 v35, 0xffff0000, v97
	v_lshlrev_b32_e32 v36, 16, v98
	v_and_b32_e32 v37, 0xffff0000, v98
	v_lshlrev_b32_e32 v38, 16, v99
	v_and_b32_e32 v39, 0xffff0000, v99
	v_lshlrev_b32_e32 v40, 16, v100
	v_and_b32_e32 v41, 0xffff0000, v100
	v_lshlrev_b32_e32 v42, 16, v101
	v_and_b32_e32 v43, 0xffff0000, v101
	v_lshlrev_b32_e32 v44, 16, v102
	v_and_b32_e32 v45, 0xffff0000, v102
	v_lshlrev_b32_e32 v46, 16, v103
	v_and_b32_e32 v47, 0xffff0000, v103
	v_lshlrev_b32_e32 v48, 16, v104
	v_and_b32_e32 v49, 0xffff0000, v104
	v_lshlrev_b32_e32 v50, 16, v105
	v_and_b32_e32 v51, 0xffff0000, v105
	v_lshlrev_b32_e32 v52, 16, v106
	v_and_b32_e32 v53, 0xffff0000, v106
	v_lshlrev_b32_e32 v54, 16, v107
	v_and_b32_e32 v55, 0xffff0000, v107
	v_lshlrev_b32_e32 v56, 16, v108
	v_and_b32_e32 v57, 0xffff0000, v108
	v_lshlrev_b32_e32 v58, 16, v109
	v_and_b32_e32 v59, 0xffff0000, v109
	v_lshlrev_b32_e32 v60, 16, v110
	v_and_b32_e32 v61, 0xffff0000, v110
	v_lshlrev_b32_e32 v62, 16, v111
	v_and_b32_e32 v63, 0xffff0000, v111
	s_nop 1
	v_mfma_f32_16x16x4_f32 v[112:115], v0, v32, 0
	v_mfma_f32_16x16x4_f32 v[112:115], v1, v33, v[112:115]
	v_mfma_f32_16x16x4_f32 v[112:115], v2, v34, v[112:115]
	v_mfma_f32_16x16x4_f32 v[112:115], v3, v35, v[112:115]
	v_mfma_f32_16x16x4_f32 v[112:115], v4, v36, v[112:115]
	v_mfma_f32_16x16x4_f32 v[112:115], v5, v37, v[112:115]
	v_mfma_f32_16x16x4_f32 v[112:115], v6, v38, v[112:115]
	v_mfma_f32_16x16x4_f32 v[112:115], v7, v39, v[112:115]
	v_mfma_f32_16x16x4_f32 v[112:115], v8, v40, v[112:115]
	v_mfma_f32_16x16x4_f32 v[112:115], v9, v41, v[112:115]
	v_mfma_f32_16x16x4_f32 v[112:115], v10, v42, v[112:115]
	v_mfma_f32_16x16x4_f32 v[112:115], v11, v43, v[112:115]
	v_mfma_f32_16x16x4_f32 v[112:115], v12, v44, v[112:115]
	v_mfma_f32_16x16x4_f32 v[112:115], v13, v45, v[112:115]
	v_mfma_f32_16x16x4_f32 v[112:115], v14, v46, v[112:115]
	v_mfma_f32_16x16x4_f32 v[112:115], v15, v47, v[112:115]
	v_mfma_f32_16x16x4_f32 v[112:115], v16, v48, v[112:115]
	v_mfma_f32_16x16x4_f32 v[112:115], v17, v49, v[112:115]
	v_mfma_f32_16x16x4_f32 v[112:115], v18, v50, v[112:115]
	v_mfma_f32_16x16x4_f32 v[112:115], v19, v51, v[112:115]
	v_mfma_f32_16x16x4_f32 v[112:115], v20, v52, v[112:115]
	v_mfma_f32_16x16x4_f32 v[112:115], v21, v53, v[112:115]
	v_mfma_f32_16x16x4_f32 v[112:115], v22, v54, v[112:115]
	v_mfma_f32_16x16x4_f32 v[112:115], v23, v55, v[112:115]
	v_mfma_f32_16x16x4_f32 v[112:115], v24, v56, v[112:115]
	v_mfma_f32_16x16x4_f32 v[112:115], v25, v57, v[112:115]
	v_mfma_f32_16x16x4_f32 v[112:115], v26, v58, v[112:115]
	v_mfma_f32_16x16x4_f32 v[112:115], v27, v59, v[112:115]
	v_mfma_f32_16x16x4_f32 v[112:115], v28, v60, v[112:115]
	v_mfma_f32_16x16x4_f32 v[112:115], v29, v61, v[112:115]
	v_mfma_f32_16x16x4_f32 v[112:115], v30, v62, v[112:115]
	v_mfma_f32_16x16x4_f32 v[112:115], v31, v63, v[112:115]
	s_nop 10
	ds_bpermute_b32 v116, v201, v112
	ds_bpermute_b32 v117, v201, v113
	ds_bpermute_b32 v118, v201, v114
	ds_bpermute_b32 v119, v201, v115
	s_waitcnt lgkmcnt(0)
	s_cmp_gt_u32 s15, 0
	s_cselect_b64 s[44:45], -1, 0
	v_cndmask_b32_e64 v112, v134, v112, s[44:45]
	s_cmp_gt_u32 s15, 1
	s_cselect_b64 s[46:47], -1, 0
	v_cndmask_b32_e64 v113, v134, v113, s[46:47]
	s_cmp_gt_u32 s15, 2
	s_cselect_b64 s[56:57], -1, 0
	v_cndmask_b32_e64 v114, v134, v114, s[56:57]
	s_cmp_gt_u32 s15, 3
	s_cselect_b64 s[58:59], -1, 0
	v_cndmask_b32_e64 v115, v134, v115, s[58:59]
	s_cmp_gt_u32 s15, 4
	s_cselect_b64 s[44:45], -1, 0
	v_cndmask_b32_e64 v116, v134, v116, s[44:45]
	s_cmp_gt_u32 s15, 5
	s_cselect_b64 s[46:47], -1, 0
	v_cndmask_b32_e64 v117, v134, v117, s[46:47]
	s_cmp_gt_u32 s15, 6
	s_cselect_b64 s[56:57], -1, 0
	v_cndmask_b32_e64 v118, v134, v118, s[56:57]
	v_mov_b32_e32 v159, 0
	v_mov_b32_e32 v157, v134
	v_mov_b32_e32 v158, 0
	v_cmp_gt_f32_e32 vcc, v112, v157
	s_nop 1
	v_cndmask_b32_e32 v157, v157, v112, vcc
	v_cndmask_b32_e64 v158, v158, 0, vcc
	v_cmp_gt_f32_e32 vcc, v113, v157
	s_nop 1
	v_cndmask_b32_e32 v157, v157, v113, vcc
	v_cndmask_b32_e64 v158, v158, 1, vcc
	v_cmp_gt_f32_e32 vcc, v114, v157
	s_nop 1
	v_cndmask_b32_e32 v157, v157, v114, vcc
	v_cndmask_b32_e64 v158, v158, 2, vcc
	v_cmp_gt_f32_e32 vcc, v115, v157
	s_nop 1
	v_cndmask_b32_e32 v157, v157, v115, vcc
	v_cndmask_b32_e64 v158, v158, 3, vcc
	v_cmp_gt_f32_e32 vcc, v116, v157
	s_nop 1
	v_cndmask_b32_e32 v157, v157, v116, vcc
	v_cndmask_b32_e64 v158, v158, 4, vcc
	v_cmp_gt_f32_e32 vcc, v117, v157
	s_nop 1
	v_cndmask_b32_e32 v157, v157, v117, vcc
	v_cndmask_b32_e64 v158, v158, 5, vcc
	v_cmp_gt_f32_e32 vcc, v118, v157
	s_nop 1
	v_cndmask_b32_e32 v157, v157, v118, vcc
	v_cndmask_b32_e64 v158, v158, 6, vcc
	v_lshlrev_b32_e64 v160, v158, 1
	v_or_b32_e32 v159, v159, v160
	v_cmp_eq_u32_e64 s[44:45], 0, v158
	v_cmp_eq_u32_e64 s[46:47], 1, v158
	v_cmp_eq_u32_e64 s[56:57], 2, v158
	v_cmp_eq_u32_e64 s[58:59], 3, v158
	s_nop 1
	v_cndmask_b32_e64 v112, v112, v134, s[44:45]
	v_cndmask_b32_e64 v113, v113, v134, s[46:47]
	v_cndmask_b32_e64 v114, v114, v134, s[56:57]
	v_cndmask_b32_e64 v115, v115, v134, s[58:59]
	v_cmp_eq_u32_e64 s[44:45], 4, v158
	v_cmp_eq_u32_e64 s[46:47], 5, v158
	v_cmp_eq_u32_e64 s[56:57], 6, v158
	s_nop 1
	v_cndmask_b32_e64 v116, v116, v134, s[44:45]
	v_cndmask_b32_e64 v117, v117, v134, s[46:47]
	v_cndmask_b32_e64 v118, v118, v134, s[56:57]
	v_mov_b32_e32 v157, v134
	v_mov_b32_e32 v158, 0
	v_cmp_gt_f32_e32 vcc, v112, v157
	s_nop 1
	v_cndmask_b32_e32 v157, v157, v112, vcc
	v_cndmask_b32_e64 v158, v158, 0, vcc
	v_cmp_gt_f32_e32 vcc, v113, v157
	s_nop 1
	v_cndmask_b32_e32 v157, v157, v113, vcc
	v_cndmask_b32_e64 v158, v158, 1, vcc
	v_cmp_gt_f32_e32 vcc, v114, v157
	s_nop 1
	v_cndmask_b32_e32 v157, v157, v114, vcc
	v_cndmask_b32_e64 v158, v158, 2, vcc
	v_cmp_gt_f32_e32 vcc, v115, v157
	s_nop 1
	v_cndmask_b32_e32 v157, v157, v115, vcc
	v_cndmask_b32_e64 v158, v158, 3, vcc
	v_cmp_gt_f32_e32 vcc, v116, v157
	s_nop 1
	v_cndmask_b32_e32 v157, v157, v116, vcc
	v_cndmask_b32_e64 v158, v158, 4, vcc
	v_cmp_gt_f32_e32 vcc, v117, v157
	s_nop 1
	v_cndmask_b32_e32 v157, v157, v117, vcc
	v_cndmask_b32_e64 v158, v158, 5, vcc
	v_cmp_gt_f32_e32 vcc, v118, v157
	s_nop 1
	v_cndmask_b32_e32 v157, v157, v118, vcc
	v_cndmask_b32_e64 v158, v158, 6, vcc
	v_lshlrev_b32_e64 v160, v158, 1
	v_or_b32_e32 v159, v159, v160
	v_cmp_eq_u32_e64 s[44:45], 0, v158
	v_cmp_eq_u32_e64 s[46:47], 1, v158
	v_cmp_eq_u32_e64 s[56:57], 2, v158
	v_cmp_eq_u32_e64 s[58:59], 3, v158
	s_nop 1
	v_cndmask_b32_e64 v112, v112, v134, s[44:45]
	v_cndmask_b32_e64 v113, v113, v134, s[46:47]
	v_cndmask_b32_e64 v114, v114, v134, s[56:57]
	v_cndmask_b32_e64 v115, v115, v134, s[58:59]
	v_cmp_eq_u32_e64 s[44:45], 4, v158
	v_cmp_eq_u32_e64 s[46:47], 5, v158
	v_cmp_eq_u32_e64 s[56:57], 6, v158
	s_nop 1
	v_cndmask_b32_e64 v116, v116, v134, s[44:45]
	v_cndmask_b32_e64 v117, v117, v134, s[46:47]
	v_cndmask_b32_e64 v118, v118, v134, s[56:57]
	v_mov_b32_e32 v157, v134
	v_mov_b32_e32 v158, 0
	v_cmp_gt_f32_e32 vcc, v112, v157
	s_nop 1
	v_cndmask_b32_e32 v157, v157, v112, vcc
	v_cndmask_b32_e64 v158, v158, 0, vcc
	v_cmp_gt_f32_e32 vcc, v113, v157
	s_nop 1
	v_cndmask_b32_e32 v157, v157, v113, vcc
	v_cndmask_b32_e64 v158, v158, 1, vcc
	v_cmp_gt_f32_e32 vcc, v114, v157
	s_nop 1
	v_cndmask_b32_e32 v157, v157, v114, vcc
	v_cndmask_b32_e64 v158, v158, 2, vcc
	v_cmp_gt_f32_e32 vcc, v115, v157
	s_nop 1
	v_cndmask_b32_e32 v157, v157, v115, vcc
	v_cndmask_b32_e64 v158, v158, 3, vcc
	v_cmp_gt_f32_e32 vcc, v116, v157
	s_nop 1
	v_cndmask_b32_e32 v157, v157, v116, vcc
	v_cndmask_b32_e64 v158, v158, 4, vcc
	v_cmp_gt_f32_e32 vcc, v117, v157
	s_nop 1
	v_cndmask_b32_e32 v157, v157, v117, vcc
	v_cndmask_b32_e64 v158, v158, 5, vcc
	v_cmp_gt_f32_e32 vcc, v118, v157
	s_nop 1
	v_cndmask_b32_e32 v157, v157, v118, vcc
	v_cndmask_b32_e64 v158, v158, 6, vcc
	v_lshlrev_b32_e64 v160, v158, 1
	v_or_b32_e32 v159, v159, v160
	v_and_b32_e32 v160, 15, v165
	v_lshlrev_b32_e32 v160, 2, v160
	ds_bpermute_b32 v152, v160, v159
	s_waitcnt lgkmcnt(0)
	s_add_u32 s22, s18, 262144
	s_addc_u32 s23, s19, 0
	global_load_dwordx4 v[96:99], v141, s[22:23] offset:0
	global_load_dwordx4 v[100:103], v141, s[22:23] offset:16
	global_load_dwordx4 v[104:107], v141, s[22:23] offset:32
	global_load_dwordx4 v[108:111], v141, s[22:23] offset:48
	s_waitcnt vmcnt(0)
	v_lshlrev_b32_e32 v32, 16, v96
	v_and_b32_e32 v33, 0xffff0000, v96
	v_lshlrev_b32_e32 v34, 16, v97
	v_and_b32_e32 v35, 0xffff0000, v97
	v_lshlrev_b32_e32 v36, 16, v98
	v_and_b32_e32 v37, 0xffff0000, v98
	v_lshlrev_b32_e32 v38, 16, v99
	v_and_b32_e32 v39, 0xffff0000, v99
	v_lshlrev_b32_e32 v40, 16, v100
	v_and_b32_e32 v41, 0xffff0000, v100
	v_lshlrev_b32_e32 v42, 16, v101
	v_and_b32_e32 v43, 0xffff0000, v101
	v_lshlrev_b32_e32 v44, 16, v102
	v_and_b32_e32 v45, 0xffff0000, v102
	v_lshlrev_b32_e32 v46, 16, v103
	v_and_b32_e32 v47, 0xffff0000, v103
	v_lshlrev_b32_e32 v48, 16, v104
	v_and_b32_e32 v49, 0xffff0000, v104
	v_lshlrev_b32_e32 v50, 16, v105
	v_and_b32_e32 v51, 0xffff0000, v105
	v_lshlrev_b32_e32 v52, 16, v106
	v_and_b32_e32 v53, 0xffff0000, v106
	v_lshlrev_b32_e32 v54, 16, v107
	v_and_b32_e32 v55, 0xffff0000, v107
	v_lshlrev_b32_e32 v56, 16, v108
	v_and_b32_e32 v57, 0xffff0000, v108
	v_lshlrev_b32_e32 v58, 16, v109
	v_and_b32_e32 v59, 0xffff0000, v109
	v_lshlrev_b32_e32 v60, 16, v110
	v_and_b32_e32 v61, 0xffff0000, v110
	v_lshlrev_b32_e32 v62, 16, v111
	v_and_b32_e32 v63, 0xffff0000, v111
	s_nop 1
	v_mfma_f32_16x16x4_f32 v[112:115], v0, v32, 0
	v_mfma_f32_16x16x4_f32 v[112:115], v1, v33, v[112:115]
	v_mfma_f32_16x16x4_f32 v[112:115], v2, v34, v[112:115]
	v_mfma_f32_16x16x4_f32 v[112:115], v3, v35, v[112:115]
	v_mfma_f32_16x16x4_f32 v[112:115], v4, v36, v[112:115]
	v_mfma_f32_16x16x4_f32 v[112:115], v5, v37, v[112:115]
	v_mfma_f32_16x16x4_f32 v[112:115], v6, v38, v[112:115]
	v_mfma_f32_16x16x4_f32 v[112:115], v7, v39, v[112:115]
	v_mfma_f32_16x16x4_f32 v[112:115], v8, v40, v[112:115]
	v_mfma_f32_16x16x4_f32 v[112:115], v9, v41, v[112:115]
	v_mfma_f32_16x16x4_f32 v[112:115], v10, v42, v[112:115]
	v_mfma_f32_16x16x4_f32 v[112:115], v11, v43, v[112:115]
	v_mfma_f32_16x16x4_f32 v[112:115], v12, v44, v[112:115]
	v_mfma_f32_16x16x4_f32 v[112:115], v13, v45, v[112:115]
	v_mfma_f32_16x16x4_f32 v[112:115], v14, v46, v[112:115]
	v_mfma_f32_16x16x4_f32 v[112:115], v15, v47, v[112:115]
	v_mfma_f32_16x16x4_f32 v[112:115], v16, v48, v[112:115]
	v_mfma_f32_16x16x4_f32 v[112:115], v17, v49, v[112:115]
	v_mfma_f32_16x16x4_f32 v[112:115], v18, v50, v[112:115]
	v_mfma_f32_16x16x4_f32 v[112:115], v19, v51, v[112:115]
	v_mfma_f32_16x16x4_f32 v[112:115], v20, v52, v[112:115]
	v_mfma_f32_16x16x4_f32 v[112:115], v21, v53, v[112:115]
	v_mfma_f32_16x16x4_f32 v[112:115], v22, v54, v[112:115]
	v_mfma_f32_16x16x4_f32 v[112:115], v23, v55, v[112:115]
	v_mfma_f32_16x16x4_f32 v[112:115], v24, v56, v[112:115]
	v_mfma_f32_16x16x4_f32 v[112:115], v25, v57, v[112:115]
	v_mfma_f32_16x16x4_f32 v[112:115], v26, v58, v[112:115]
	v_mfma_f32_16x16x4_f32 v[112:115], v27, v59, v[112:115]
	v_mfma_f32_16x16x4_f32 v[112:115], v28, v60, v[112:115]
	v_mfma_f32_16x16x4_f32 v[112:115], v29, v61, v[112:115]
	v_mfma_f32_16x16x4_f32 v[112:115], v30, v62, v[112:115]
	v_mfma_f32_16x16x4_f32 v[112:115], v31, v63, v[112:115]
	s_nop 10
	ds_bpermute_b32 v116, v201, v112
	ds_bpermute_b32 v117, v201, v113
	ds_bpermute_b32 v118, v201, v114
	ds_bpermute_b32 v119, v201, v115
	s_waitcnt lgkmcnt(0)
	s_cmp_gt_u32 s15, 0
	s_cselect_b64 s[44:45], -1, 0
	v_cndmask_b32_e64 v112, v134, v112, s[44:45]
	s_cmp_gt_u32 s15, 1
	s_cselect_b64 s[46:47], -1, 0
	v_cndmask_b32_e64 v113, v134, v113, s[46:47]
	s_cmp_gt_u32 s15, 2
	s_cselect_b64 s[56:57], -1, 0
	v_cndmask_b32_e64 v114, v134, v114, s[56:57]
	s_cmp_gt_u32 s15, 3
	s_cselect_b64 s[58:59], -1, 0
	v_cndmask_b32_e64 v115, v134, v115, s[58:59]
	s_cmp_gt_u32 s15, 4
	s_cselect_b64 s[44:45], -1, 0
	v_cndmask_b32_e64 v116, v134, v116, s[44:45]
	s_cmp_gt_u32 s15, 5
	s_cselect_b64 s[46:47], -1, 0
	v_cndmask_b32_e64 v117, v134, v117, s[46:47]
	s_cmp_gt_u32 s15, 6
	s_cselect_b64 s[56:57], -1, 0
	v_cndmask_b32_e64 v118, v134, v118, s[56:57]
	v_mov_b32_e32 v159, 0
	v_mov_b32_e32 v157, v134
	v_mov_b32_e32 v158, 0
	v_cmp_gt_f32_e32 vcc, v112, v157
	s_nop 1
	v_cndmask_b32_e32 v157, v157, v112, vcc
	v_cndmask_b32_e64 v158, v158, 0, vcc
	v_cmp_gt_f32_e32 vcc, v113, v157
	s_nop 1
	v_cndmask_b32_e32 v157, v157, v113, vcc
	v_cndmask_b32_e64 v158, v158, 1, vcc
	v_cmp_gt_f32_e32 vcc, v114, v157
	s_nop 1
	v_cndmask_b32_e32 v157, v157, v114, vcc
	v_cndmask_b32_e64 v158, v158, 2, vcc
	v_cmp_gt_f32_e32 vcc, v115, v157
	s_nop 1
	v_cndmask_b32_e32 v157, v157, v115, vcc
	v_cndmask_b32_e64 v158, v158, 3, vcc
	v_cmp_gt_f32_e32 vcc, v116, v157
	s_nop 1
	v_cndmask_b32_e32 v157, v157, v116, vcc
	v_cndmask_b32_e64 v158, v158, 4, vcc
	v_cmp_gt_f32_e32 vcc, v117, v157
	s_nop 1
	v_cndmask_b32_e32 v157, v157, v117, vcc
	v_cndmask_b32_e64 v158, v158, 5, vcc
	v_cmp_gt_f32_e32 vcc, v118, v157
	s_nop 1
	v_cndmask_b32_e32 v157, v157, v118, vcc
	v_cndmask_b32_e64 v158, v158, 6, vcc
	v_lshlrev_b32_e64 v160, v158, 1
	v_or_b32_e32 v159, v159, v160
	v_cmp_eq_u32_e64 s[44:45], 0, v158
	v_cmp_eq_u32_e64 s[46:47], 1, v158
	v_cmp_eq_u32_e64 s[56:57], 2, v158
	v_cmp_eq_u32_e64 s[58:59], 3, v158
	s_nop 1
	v_cndmask_b32_e64 v112, v112, v134, s[44:45]
	v_cndmask_b32_e64 v113, v113, v134, s[46:47]
	v_cndmask_b32_e64 v114, v114, v134, s[56:57]
	v_cndmask_b32_e64 v115, v115, v134, s[58:59]
	v_cmp_eq_u32_e64 s[44:45], 4, v158
	v_cmp_eq_u32_e64 s[46:47], 5, v158
	v_cmp_eq_u32_e64 s[56:57], 6, v158
	s_nop 1
	v_cndmask_b32_e64 v116, v116, v134, s[44:45]
	v_cndmask_b32_e64 v117, v117, v134, s[46:47]
	v_cndmask_b32_e64 v118, v118, v134, s[56:57]
	v_mov_b32_e32 v157, v134
	v_mov_b32_e32 v158, 0
	v_cmp_gt_f32_e32 vcc, v112, v157
	s_nop 1
	v_cndmask_b32_e32 v157, v157, v112, vcc
	v_cndmask_b32_e64 v158, v158, 0, vcc
	v_cmp_gt_f32_e32 vcc, v113, v157
	s_nop 1
	v_cndmask_b32_e32 v157, v157, v113, vcc
	v_cndmask_b32_e64 v158, v158, 1, vcc
	v_cmp_gt_f32_e32 vcc, v114, v157
	s_nop 1
	v_cndmask_b32_e32 v157, v157, v114, vcc
	v_cndmask_b32_e64 v158, v158, 2, vcc
	v_cmp_gt_f32_e32 vcc, v115, v157
	s_nop 1
	v_cndmask_b32_e32 v157, v157, v115, vcc
	v_cndmask_b32_e64 v158, v158, 3, vcc
	v_cmp_gt_f32_e32 vcc, v116, v157
	s_nop 1
	v_cndmask_b32_e32 v157, v157, v116, vcc
	v_cndmask_b32_e64 v158, v158, 4, vcc
	v_cmp_gt_f32_e32 vcc, v117, v157
	s_nop 1
	v_cndmask_b32_e32 v157, v157, v117, vcc
	v_cndmask_b32_e64 v158, v158, 5, vcc
	v_cmp_gt_f32_e32 vcc, v118, v157
	s_nop 1
	v_cndmask_b32_e32 v157, v157, v118, vcc
	v_cndmask_b32_e64 v158, v158, 6, vcc
	v_lshlrev_b32_e64 v160, v158, 1
	v_or_b32_e32 v159, v159, v160
	v_cmp_eq_u32_e64 s[44:45], 0, v158
	v_cmp_eq_u32_e64 s[46:47], 1, v158
	v_cmp_eq_u32_e64 s[56:57], 2, v158
	v_cmp_eq_u32_e64 s[58:59], 3, v158
	s_nop 1
	v_cndmask_b32_e64 v112, v112, v134, s[44:45]
	v_cndmask_b32_e64 v113, v113, v134, s[46:47]
	v_cndmask_b32_e64 v114, v114, v134, s[56:57]
	v_cndmask_b32_e64 v115, v115, v134, s[58:59]
	v_cmp_eq_u32_e64 s[44:45], 4, v158
	v_cmp_eq_u32_e64 s[46:47], 5, v158
	v_cmp_eq_u32_e64 s[56:57], 6, v158
	s_nop 1
	v_cndmask_b32_e64 v116, v116, v134, s[44:45]
	v_cndmask_b32_e64 v117, v117, v134, s[46:47]
	v_cndmask_b32_e64 v118, v118, v134, s[56:57]
	v_mov_b32_e32 v157, v134
	v_mov_b32_e32 v158, 0
	v_cmp_gt_f32_e32 vcc, v112, v157
	s_nop 1
	v_cndmask_b32_e32 v157, v157, v112, vcc
	v_cndmask_b32_e64 v158, v158, 0, vcc
	v_cmp_gt_f32_e32 vcc, v113, v157
	s_nop 1
	v_cndmask_b32_e32 v157, v157, v113, vcc
	v_cndmask_b32_e64 v158, v158, 1, vcc
	v_cmp_gt_f32_e32 vcc, v114, v157
	s_nop 1
	v_cndmask_b32_e32 v157, v157, v114, vcc
	v_cndmask_b32_e64 v158, v158, 2, vcc
	v_cmp_gt_f32_e32 vcc, v115, v157
	s_nop 1
	v_cndmask_b32_e32 v157, v157, v115, vcc
	v_cndmask_b32_e64 v158, v158, 3, vcc
	v_cmp_gt_f32_e32 vcc, v116, v157
	s_nop 1
	v_cndmask_b32_e32 v157, v157, v116, vcc
	v_cndmask_b32_e64 v158, v158, 4, vcc
	v_cmp_gt_f32_e32 vcc, v117, v157
	s_nop 1
	v_cndmask_b32_e32 v157, v157, v117, vcc
	v_cndmask_b32_e64 v158, v158, 5, vcc
	v_cmp_gt_f32_e32 vcc, v118, v157
	s_nop 1
	v_cndmask_b32_e32 v157, v157, v118, vcc
	v_cndmask_b32_e64 v158, v158, 6, vcc
	v_lshlrev_b32_e64 v160, v158, 1
	v_or_b32_e32 v159, v159, v160
	v_and_b32_e32 v160, 15, v165
	v_lshlrev_b32_e32 v160, 2, v160
	ds_bpermute_b32 v153, v160, v159
	s_waitcnt lgkmcnt(0)
	s_branch .Lmb_sel_done
.Lmb_sel_small:
	s_lshl_b32 s25, 1, s15
	s_sub_u32 s25, s25, 1
	v_mov_b32_e32 v152, s25
	v_mov_b32_e32 v153, s25
.Lmb_sel_done:
	v_lshl_add_u32 v141, v140, 4, v139
	s_add_u32 s22, s18, 0
	s_addc_u32 s23, s19, 0
	global_load_dwordx4 v[64:67], v141, s[22:23] offset:0
	global_load_dwordx4 v[68:71], v141, s[22:23] offset:64
	global_load_dwordx4 v[72:75], v141, s[22:23] offset:128
	global_load_dwordx4 v[76:79], v141, s[22:23] offset:192
	s_add_u32 s22, s18, 262144
	s_addc_u32 s23, s19, 0
	global_load_dwordx4 v[80:83], v141, s[22:23] offset:0
	global_load_dwordx4 v[84:87], v141, s[22:23] offset:64
	global_load_dwordx4 v[88:91], v141, s[22:23] offset:128
	global_load_dwordx4 v[92:95], v141, s[22:23] offset:192
	s_waitcnt vmcnt(0)
	v_lshlrev_b32_e32 v142, 16, v64
	v_and_b32_e32 v143, 0xffff0000, v64
	v_mul_f32_e32 v142, s75, v142
	v_mul_f32_e32 v143, s75, v143
	v_cvt_pk_bf16_f32 v64, v142, v143
	v_lshlrev_b32_e32 v142, 16, v65
	v_and_b32_e32 v143, 0xffff0000, v65
	v_mul_f32_e32 v142, s75, v142
	v_mul_f32_e32 v143, s75, v143
	v_cvt_pk_bf16_f32 v65, v142, v143
	v_lshlrev_b32_e32 v142, 16, v66
	v_and_b32_e32 v143, 0xffff0000, v66
	v_mul_f32_e32 v142, s75, v142
	v_mul_f32_e32 v143, s75, v143
	v_cvt_pk_bf16_f32 v66, v142, v143
	v_lshlrev_b32_e32 v142, 16, v67
	v_and_b32_e32 v143, 0xffff0000, v67
	v_mul_f32_e32 v142, s75, v142
	v_mul_f32_e32 v143, s75, v143
	v_cvt_pk_bf16_f32 v67, v142, v143
	v_lshlrev_b32_e32 v142, 16, v68
	v_and_b32_e32 v143, 0xffff0000, v68
	v_mul_f32_e32 v142, s75, v142
	v_mul_f32_e32 v143, s75, v143
	v_cvt_pk_bf16_f32 v68, v142, v143
	v_lshlrev_b32_e32 v142, 16, v69
	v_and_b32_e32 v143, 0xffff0000, v69
	v_mul_f32_e32 v142, s75, v142
	v_mul_f32_e32 v143, s75, v143
	v_cvt_pk_bf16_f32 v69, v142, v143
	v_lshlrev_b32_e32 v142, 16, v70
	v_and_b32_e32 v143, 0xffff0000, v70
	v_mul_f32_e32 v142, s75, v142
	v_mul_f32_e32 v143, s75, v143
	v_cvt_pk_bf16_f32 v70, v142, v143
	v_lshlrev_b32_e32 v142, 16, v71
	v_and_b32_e32 v143, 0xffff0000, v71
	v_mul_f32_e32 v142, s75, v142
	v_mul_f32_e32 v143, s75, v143
	v_cvt_pk_bf16_f32 v71, v142, v143
	v_lshlrev_b32_e32 v142, 16, v72
	v_and_b32_e32 v143, 0xffff0000, v72
	v_mul_f32_e32 v142, s75, v142
	v_mul_f32_e32 v143, s75, v143
	v_cvt_pk_bf16_f32 v72, v142, v143
	v_lshlrev_b32_e32 v142, 16, v73
	v_and_b32_e32 v143, 0xffff0000, v73
	v_mul_f32_e32 v142, s75, v142
	v_mul_f32_e32 v143, s75, v143
	v_cvt_pk_bf16_f32 v73, v142, v143
	v_lshlrev_b32_e32 v142, 16, v74
	v_and_b32_e32 v143, 0xffff0000, v74
	v_mul_f32_e32 v142, s75, v142
	v_mul_f32_e32 v143, s75, v143
	v_cvt_pk_bf16_f32 v74, v142, v143
	v_lshlrev_b32_e32 v142, 16, v75
	v_and_b32_e32 v143, 0xffff0000, v75
	v_mul_f32_e32 v142, s75, v142
	v_mul_f32_e32 v143, s75, v143
	v_cvt_pk_bf16_f32 v75, v142, v143
	v_lshlrev_b32_e32 v142, 16, v76
	v_and_b32_e32 v143, 0xffff0000, v76
	v_mul_f32_e32 v142, s75, v142
	v_mul_f32_e32 v143, s75, v143
	v_cvt_pk_bf16_f32 v76, v142, v143
	v_lshlrev_b32_e32 v142, 16, v77
	v_and_b32_e32 v143, 0xffff0000, v77
	v_mul_f32_e32 v142, s75, v142
	v_mul_f32_e32 v143, s75, v143
	v_cvt_pk_bf16_f32 v77, v142, v143
	v_lshlrev_b32_e32 v142, 16, v78
	v_and_b32_e32 v143, 0xffff0000, v78
	v_mul_f32_e32 v142, s75, v142
	v_mul_f32_e32 v143, s75, v143
	v_cvt_pk_bf16_f32 v78, v142, v143
	v_lshlrev_b32_e32 v142, 16, v79
	v_and_b32_e32 v143, 0xffff0000, v79
	v_mul_f32_e32 v142, s75, v142
	v_mul_f32_e32 v143, s75, v143
	v_cvt_pk_bf16_f32 v79, v142, v143
	v_lshlrev_b32_e32 v142, 16, v80
	v_and_b32_e32 v143, 0xffff0000, v80
	v_mul_f32_e32 v142, s75, v142
	v_mul_f32_e32 v143, s75, v143
	v_cvt_pk_bf16_f32 v80, v142, v143
	v_lshlrev_b32_e32 v142, 16, v81
	v_and_b32_e32 v143, 0xffff0000, v81
	v_mul_f32_e32 v142, s75, v142
	v_mul_f32_e32 v143, s75, v143
	v_cvt_pk_bf16_f32 v81, v142, v143
	v_lshlrev_b32_e32 v142, 16, v82
	v_and_b32_e32 v143, 0xffff0000, v82
	v_mul_f32_e32 v142, s75, v142
	v_mul_f32_e32 v143, s75, v143
	v_cvt_pk_bf16_f32 v82, v142, v143
	v_lshlrev_b32_e32 v142, 16, v83
	v_and_b32_e32 v143, 0xffff0000, v83
	v_mul_f32_e32 v142, s75, v142
	v_mul_f32_e32 v143, s75, v143
	v_cvt_pk_bf16_f32 v83, v142, v143
	v_lshlrev_b32_e32 v142, 16, v84
	v_and_b32_e32 v143, 0xffff0000, v84
	v_mul_f32_e32 v142, s75, v142
	v_mul_f32_e32 v143, s75, v143
	v_cvt_pk_bf16_f32 v84, v142, v143
	v_lshlrev_b32_e32 v142, 16, v85
	v_and_b32_e32 v143, 0xffff0000, v85
	v_mul_f32_e32 v142, s75, v142
	v_mul_f32_e32 v143, s75, v143
	v_cvt_pk_bf16_f32 v85, v142, v143
	v_lshlrev_b32_e32 v142, 16, v86
	v_and_b32_e32 v143, 0xffff0000, v86
	v_mul_f32_e32 v142, s75, v142
	v_mul_f32_e32 v143, s75, v143
	v_cvt_pk_bf16_f32 v86, v142, v143
	v_lshlrev_b32_e32 v142, 16, v87
	v_and_b32_e32 v143, 0xffff0000, v87
	v_mul_f32_e32 v142, s75, v142
	v_mul_f32_e32 v143, s75, v143
	v_cvt_pk_bf16_f32 v87, v142, v143
	v_lshlrev_b32_e32 v142, 16, v88
	v_and_b32_e32 v143, 0xffff0000, v88
	v_mul_f32_e32 v142, s75, v142
	v_mul_f32_e32 v143, s75, v143
	v_cvt_pk_bf16_f32 v88, v142, v143
	v_lshlrev_b32_e32 v142, 16, v89
	v_and_b32_e32 v143, 0xffff0000, v89
	v_mul_f32_e32 v142, s75, v142
	v_mul_f32_e32 v143, s75, v143
	v_cvt_pk_bf16_f32 v89, v142, v143
	v_lshlrev_b32_e32 v142, 16, v90
	v_and_b32_e32 v143, 0xffff0000, v90
	v_mul_f32_e32 v142, s75, v142
	v_mul_f32_e32 v143, s75, v143
	v_cvt_pk_bf16_f32 v90, v142, v143
	v_lshlrev_b32_e32 v142, 16, v91
	v_and_b32_e32 v143, 0xffff0000, v91
	v_mul_f32_e32 v142, s75, v142
	v_mul_f32_e32 v143, s75, v143
	v_cvt_pk_bf16_f32 v91, v142, v143
	v_lshlrev_b32_e32 v142, 16, v92
	v_and_b32_e32 v143, 0xffff0000, v92
	v_mul_f32_e32 v142, s75, v142
	v_mul_f32_e32 v143, s75, v143
	v_cvt_pk_bf16_f32 v92, v142, v143
	v_lshlrev_b32_e32 v142, 16, v93
	v_and_b32_e32 v143, 0xffff0000, v93
	v_mul_f32_e32 v142, s75, v142
	v_mul_f32_e32 v143, s75, v143
	v_cvt_pk_bf16_f32 v93, v142, v143
	v_lshlrev_b32_e32 v142, 16, v94
	v_and_b32_e32 v143, 0xffff0000, v94
	v_mul_f32_e32 v142, s75, v142
	v_mul_f32_e32 v143, s75, v143
	v_cvt_pk_bf16_f32 v94, v142, v143
	v_lshlrev_b32_e32 v142, 16, v95
	v_and_b32_e32 v143, 0xffff0000, v95
	v_mul_f32_e32 v142, s75, v142
	v_mul_f32_e32 v143, s75, v143
	v_cvt_pk_bf16_f32 v95, v142, v143
	v_mov_b32_e32 v0, 0
	v_mov_b32_e32 v1, 0
	v_mov_b32_e32 v2, 0
	v_mov_b32_e32 v3, 0
	v_mov_b32_e32 v4, 0
	v_mov_b32_e32 v5, 0
	v_mov_b32_e32 v6, 0
	v_mov_b32_e32 v7, 0
	v_mov_b32_e32 v8, 0
	v_mov_b32_e32 v9, 0
	v_mov_b32_e32 v10, 0
	v_mov_b32_e32 v11, 0
	v_mov_b32_e32 v12, 0
	v_mov_b32_e32 v13, 0
	v_mov_b32_e32 v14, 0
	v_mov_b32_e32 v15, 0
	v_mov_b32_e32 v16, 0
	v_mov_b32_e32 v17, 0
	v_mov_b32_e32 v18, 0
	v_mov_b32_e32 v19, 0
	v_mov_b32_e32 v20, 0
	v_mov_b32_e32 v21, 0
	v_mov_b32_e32 v22, 0
	v_mov_b32_e32 v23, 0
	v_mov_b32_e32 v24, 0
	v_mov_b32_e32 v25, 0
	v_mov_b32_e32 v26, 0
	v_mov_b32_e32 v27, 0
	v_mov_b32_e32 v28, 0
	v_mov_b32_e32 v29, 0
	v_mov_b32_e32 v30, 0
	v_mov_b32_e32 v31, 0
	v_mov_b32_e32 v32, 0
	v_mov_b32_e32 v33, 0
	v_mov_b32_e32 v34, 0
	v_mov_b32_e32 v35, 0
	v_mov_b32_e32 v36, 0
	v_mov_b32_e32 v37, 0
	v_mov_b32_e32 v38, 0
	v_mov_b32_e32 v39, 0
	v_mov_b32_e32 v40, 0
	v_mov_b32_e32 v41, 0
	v_mov_b32_e32 v42, 0
	v_mov_b32_e32 v43, 0
	v_mov_b32_e32 v44, 0
	v_mov_b32_e32 v45, 0
	v_mov_b32_e32 v46, 0
	v_mov_b32_e32 v47, 0
	v_mov_b32_e32 v48, 0
	v_mov_b32_e32 v49, 0
	v_mov_b32_e32 v50, 0
	v_mov_b32_e32 v51, 0
	v_mov_b32_e32 v52, 0
	v_mov_b32_e32 v53, 0
	v_mov_b32_e32 v54, 0
	v_mov_b32_e32 v55, 0
	v_mov_b32_e32 v56, 0
	v_mov_b32_e32 v57, 0
	v_mov_b32_e32 v58, 0
	v_mov_b32_e32 v59, 0
	v_mov_b32_e32 v60, 0
	v_mov_b32_e32 v61, 0
	v_mov_b32_e32 v62, 0
	v_mov_b32_e32 v63, 0
	v_mov_b32_e32 v148, 0xf149f2ca
	v_mov_b32_e32 v150, 0
	v_mov_b32_e32 v149, 0xf149f2ca
	v_mov_b32_e32 v151, 0
	v_xor_b32_e32 v130, 65536, v130
	v_xor_b32_e32 v131, 65536, v131
	s_waitcnt vmcnt(0)
	ds_write_b128 v130, v[168:171]
	ds_write_b128 v130, v[172:175] offset:8704
	ds_write_b128 v131, v[176:179]
	ds_write_b128 v131, v[180:183] offset:9216
	v_xor_b32_e32 v130, 65536, v130
	v_xor_b32_e32 v131, 65536, v131
	s_mov_b32 s25, 1
	s_lshl_b32 s33, s15, 2
	s_add_u32 s33, s33, s25
	s_sub_u32 s26, s25, 4
	s_cmp_lt_u32 s25, 4
	s_cselect_b32 s26, s33, s26
	s_lshl_b32 s33, s26, 20
	s_add_u32 s20, s8, s33
	s_addc_u32 s21, s9, 0
	global_load_dwordx4 v[168:171], v132, s[20:21] offset:2048
	global_load_dwordx4 v[172:175], v133, s[20:21] offset:2048
	s_add_u32 s20, s20, 0x1000
	s_addc_u32 s21, s21, 0
	global_load_dwordx4 v[176:179], v132, s[20:21]
	global_load_dwordx4 v[180:183], v133, s[20:21]
	s_mov_b32 s17, 0
	s_waitcnt lgkmcnt(0)
	s_barrier
.Lmb_loop:
	s_add_u32 s25, s17, 1
	s_cmp_ge_u32 s25, s16
	s_cbranch_scc1 .Lmb_nostage
	s_waitcnt vmcnt(0)
	ds_write_b128 v130, v[168:171]
	ds_write_b128 v130, v[172:175] offset:8704
	ds_write_b128 v131, v[176:179]
	ds_write_b128 v131, v[180:183] offset:9216
	s_add_u32 s25, s17, 2
	s_cmp_ge_u32 s25, s16
	s_cbranch_scc1 .Lmb_nostage
	s_lshl_b32 s33, s15, 2
	s_add_u32 s33, s33, s25
	s_sub_u32 s26, s25, 4
	s_cmp_lt_u32 s25, 4
	s_cselect_b32 s26, s33, s26
	s_lshl_b32 s33, s26, 20
	s_add_u32 s20, s8, s33
	s_addc_u32 s21, s9, 0
	global_load_dwordx4 v[168:171], v132, s[20:21] offset:2048
	global_load_dwordx4 v[172:175], v133, s[20:21] offset:2048
	s_add_u32 s20, s20, 0x1000
	s_addc_u32 s21, s21, 0
	global_load_dwordx4 v[176:179], v132, s[20:21]
	global_load_dwordx4 v[180:183], v133, s[20:21]
.Lmb_nostage:
	s_cmp_ge_u32 s17, 4
	s_cbranch_scc1 .Lmb_past
	s_lshl_b32 s25, s17, 6
	s_lshl_b32 s26, s7, 5
	s_add_u32 s26, s26, 31
	s_cmp_gt_u32 s25, s26
	s_cbranch_scc1 .Lmb_iter_end
	v_max_f32_e32 v146, s73, v148
	v_max_f32_e32 v147, s73, v149
	v_subrev_u32_e32 v137, s25, v136
	v_add_u32_e32 v138, 16, v137
	s_branch .Lmb_S
.Lmb_past:
	s_sub_u32 s25, s17, 4
	s_lshr_b32 s25, s25, 2
	v_lshrrev_b32_e32 v157, s25, v152
	v_lshrrev_b32_e32 v158, s25, v153
	v_and_b32_e32 v157, 1, v157
	v_and_b32_e32 v158, 1, v158
	v_cmp_eq_u32_e64 s[44:45], 1, v157
	v_cmp_eq_u32_e64 s[46:47], 1, v158
	v_max_f32_e32 v159, s73, v148
	v_max_f32_e32 v160, s73, v149
	v_cndmask_b32_e64 v146, v135, v159, s[44:45]
	v_cndmask_b32_e64 v147, v135, v160, s[46:47]
.Lmb_S:
	v_xor_b32_e32 v184, 0x80000000, v146
	v_xor_b32_e32 v185, 0x80000000, v146
	v_xor_b32_e32 v186, 0x80000000, v146
	v_xor_b32_e32 v187, 0x80000000, v146
	v_xor_b32_e32 v188, 0x80000000, v147
	v_xor_b32_e32 v189, 0x80000000, v147
	v_xor_b32_e32 v190, 0x80000000, v147
	v_xor_b32_e32 v191, 0x80000000, v147
	ds_read_b128 v[204:207], v128 offset:0
	ds_read_b128 v[208:211], v128 offset:64
	ds_read_b128 v[212:215], v128 offset:128
	ds_read_b128 v[216:219], v128 offset:192
	ds_read_b128 v[240:243], v128 offset:4352
	ds_read_b128 v[244:247], v128 offset:4416
	ds_read_b128 v[248:251], v128 offset:4480
	ds_read_b128 v[252:255], v128 offset:4544
	s_waitcnt lgkmcnt(7)
	v_mfma_f32_16x16x32_bf16 v[96:99], v[204:207], v[64:67], v[184:187]
	v_mfma_f32_16x16x32_bf16 v[112:115], v[204:207], v[80:83], v[188:191]
	ds_read_b128 v[204:207], v128 offset:8704
	s_waitcnt lgkmcnt(7)
	v_mfma_f32_16x16x32_bf16 v[96:99], v[208:211], v[68:71], v[96:99]
	v_mfma_f32_16x16x32_bf16 v[112:115], v[208:211], v[84:87], v[112:115]
	ds_read_b128 v[208:211], v128 offset:8768
	s_waitcnt lgkmcnt(7)
	v_mfma_f32_16x16x32_bf16 v[96:99], v[212:215], v[72:75], v[96:99]
	v_mfma_f32_16x16x32_bf16 v[112:115], v[212:215], v[88:91], v[112:115]
	ds_read_b128 v[212:215], v128 offset:8832
	s_waitcnt lgkmcnt(7)
	v_mfma_f32_16x16x32_bf16 v[96:99], v[216:219], v[76:79], v[96:99]
	v_mfma_f32_16x16x32_bf16 v[112:115], v[216:219], v[92:95], v[112:115]
	ds_read_b128 v[216:219], v128 offset:8896
	s_waitcnt lgkmcnt(7)
	v_mfma_f32_16x16x32_bf16 v[100:103], v[240:243], v[64:67], v[184:187]
	v_mfma_f32_16x16x32_bf16 v[116:119], v[240:243], v[80:83], v[188:191]
	ds_read_b128 v[240:243], v128 offset:13056
	s_waitcnt lgkmcnt(7)
	v_mfma_f32_16x16x32_bf16 v[100:103], v[244:247], v[68:71], v[100:103]
	v_mfma_f32_16x16x32_bf16 v[116:119], v[244:247], v[84:87], v[116:119]
	ds_read_b128 v[244:247], v128 offset:13120
	s_waitcnt lgkmcnt(7)
	v_mfma_f32_16x16x32_bf16 v[100:103], v[248:251], v[72:75], v[100:103]
	v_mfma_f32_16x16x32_bf16 v[116:119], v[248:251], v[88:91], v[116:119]
	ds_read_b128 v[248:251], v128 offset:13184
	s_waitcnt lgkmcnt(7)
	v_mfma_f32_16x16x32_bf16 v[100:103], v[252:255], v[76:79], v[100:103]
	v_mfma_f32_16x16x32_bf16 v[116:119], v[252:255], v[92:95], v[116:119]
	ds_read_b128 v[252:255], v128 offset:13248
	s_waitcnt lgkmcnt(7)
	v_mfma_f32_16x16x32_bf16 v[104:107], v[204:207], v[64:67], v[184:187]
	v_mfma_f32_16x16x32_bf16 v[120:123], v[204:207], v[80:83], v[188:191]
	s_waitcnt lgkmcnt(6)
	v_mfma_f32_16x16x32_bf16 v[104:107], v[208:211], v[68:71], v[104:107]
	v_mfma_f32_16x16x32_bf16 v[120:123], v[208:211], v[84:87], v[120:123]
	s_waitcnt lgkmcnt(5)
	v_mfma_f32_16x16x32_bf16 v[104:107], v[212:215], v[72:75], v[104:107]
	v_mfma_f32_16x16x32_bf16 v[120:123], v[212:215], v[88:91], v[120:123]
	s_waitcnt lgkmcnt(4)
	v_mfma_f32_16x16x32_bf16 v[104:107], v[216:219], v[76:79], v[104:107]
	v_mfma_f32_16x16x32_bf16 v[120:123], v[216:219], v[92:95], v[120:123]
	s_waitcnt lgkmcnt(3)
	v_mfma_f32_16x16x32_bf16 v[108:111], v[240:243], v[64:67], v[184:187]
	v_mfma_f32_16x16x32_bf16 v[124:127], v[240:243], v[80:83], v[188:191]
	s_waitcnt lgkmcnt(2)
	v_mfma_f32_16x16x32_bf16 v[108:111], v[244:247], v[68:71], v[108:111]
	v_mfma_f32_16x16x32_bf16 v[124:127], v[244:247], v[84:87], v[124:127]
	s_waitcnt lgkmcnt(1)
	v_mfma_f32_16x16x32_bf16 v[108:111], v[248:251], v[72:75], v[108:111]
	v_mfma_f32_16x16x32_bf16 v[124:127], v[248:251], v[88:91], v[124:127]
	s_waitcnt lgkmcnt(0)
	v_mfma_f32_16x16x32_bf16 v[108:111], v[252:255], v[76:79], v[108:111]
	v_mfma_f32_16x16x32_bf16 v[124:127], v[252:255], v[92:95], v[124:127]
	ds_read_b64_tr_b16 v[204:205], v129 offset:0
	ds_read_b64_tr_b16 v[206:207], v129 offset:4608
	ds_read_b64_tr_b16 v[208:209], v129 offset:32
	ds_read_b64_tr_b16 v[210:211], v129 offset:4640
	ds_read_b64_tr_b16 v[212:213], v129 offset:64
	ds_read_b64_tr_b16 v[214:215], v129 offset:4672
	ds_read_b64_tr_b16 v[216:217], v129 offset:96
	ds_read_b64_tr_b16 v[218:219], v129 offset:4704
	ds_read_b64_tr_b16 v[240:241], v129 offset:128
	ds_read_b64_tr_b16 v[242:243], v129 offset:4736
	ds_read_b64_tr_b16 v[244:245], v129 offset:160
	ds_read_b64_tr_b16 v[246:247], v129 offset:4768
	s_cmp_ge_u32 s17, 4
	s_cbranch_scc1 .Lmb_nomask
	v_cmp_le_i32_e64 s[44:45], 0, v137
	v_cmp_le_i32_e64 s[46:47], 1, v137
	v_cmp_le_i32_e64 s[56:57], 2, v137
	v_cmp_le_i32_e64 s[58:59], 3, v137
	v_cndmask_b32_e64 v96, v134, v96, s[44:45]
	v_cndmask_b32_e64 v97, v134, v97, s[46:47]
	v_cndmask_b32_e64 v98, v134, v98, s[56:57]
	v_cndmask_b32_e64 v99, v134, v99, s[58:59]
	v_cmp_le_i32_e64 s[44:45], 16, v137
	v_cmp_le_i32_e64 s[46:47], 17, v137
	v_cmp_le_i32_e64 s[56:57], 18, v137
	v_cmp_le_i32_e64 s[58:59], 19, v137
	v_cndmask_b32_e64 v100, v134, v100, s[44:45]
	v_cndmask_b32_e64 v101, v134, v101, s[46:47]
	v_cndmask_b32_e64 v102, v134, v102, s[56:57]
	v_cndmask_b32_e64 v103, v134, v103, s[58:59]
	v_cmp_le_i32_e64 s[44:45], 32, v137
	v_cmp_le_i32_e64 s[46:47], 33, v137
	v_cmp_le_i32_e64 s[56:57], 34, v137
	v_cmp_le_i32_e64 s[58:59], 35, v137
	v_cndmask_b32_e64 v104, v134, v104, s[44:45]
	v_cndmask_b32_e64 v105, v134, v105, s[46:47]
	v_cndmask_b32_e64 v106, v134, v106, s[56:57]
	v_cndmask_b32_e64 v107, v134, v107, s[58:59]
	v_cmp_le_i32_e64 s[44:45], 48, v137
	v_cmp_le_i32_e64 s[46:47], 49, v137
	v_cmp_le_i32_e64 s[56:57], 50, v137
	v_cmp_le_i32_e64 s[58:59], 51, v137
	v_cndmask_b32_e64 v108, v134, v108, s[44:45]
	v_cndmask_b32_e64 v109, v134, v109, s[46:47]
	v_cndmask_b32_e64 v110, v134, v110, s[56:57]
	v_cndmask_b32_e64 v111, v134, v111, s[58:59]
	v_cmp_le_i32_e64 s[44:45], 0, v138
	v_cmp_le_i32_e64 s[46:47], 1, v138
	v_cmp_le_i32_e64 s[56:57], 2, v138
	v_cmp_le_i32_e64 s[58:59], 3, v138
	v_cndmask_b32_e64 v112, v134, v112, s[44:45]
	v_cndmask_b32_e64 v113, v134, v113, s[46:47]
	v_cndmask_b32_e64 v114, v134, v114, s[56:57]
	v_cndmask_b32_e64 v115, v134, v115, s[58:59]
	v_cmp_le_i32_e64 s[44:45], 16, v138
	v_cmp_le_i32_e64 s[46:47], 17, v138
	v_cmp_le_i32_e64 s[56:57], 18, v138
	v_cmp_le_i32_e64 s[58:59], 19, v138
	v_cndmask_b32_e64 v116, v134, v116, s[44:45]
	v_cndmask_b32_e64 v117, v134, v117, s[46:47]
	v_cndmask_b32_e64 v118, v134, v118, s[56:57]
	v_cndmask_b32_e64 v119, v134, v119, s[58:59]
	v_cmp_le_i32_e64 s[44:45], 32, v138
	v_cmp_le_i32_e64 s[46:47], 33, v138
	v_cmp_le_i32_e64 s[56:57], 34, v138
	v_cmp_le_i32_e64 s[58:59], 35, v138
	v_cndmask_b32_e64 v120, v134, v120, s[44:45]
	v_cndmask_b32_e64 v121, v134, v121, s[46:47]
	v_cndmask_b32_e64 v122, v134, v122, s[56:57]
	v_cndmask_b32_e64 v123, v134, v123, s[58:59]
	v_cmp_le_i32_e64 s[44:45], 48, v138
	v_cmp_le_i32_e64 s[46:47], 49, v138
	v_cmp_le_i32_e64 s[56:57], 50, v138
	v_cmp_le_i32_e64 s[58:59], 51, v138
	v_cndmask_b32_e64 v124, v134, v124, s[44:45]
	v_cndmask_b32_e64 v125, v134, v125, s[46:47]
	v_cndmask_b32_e64 v126, v134, v126, s[56:57]
	v_cndmask_b32_e64 v127, v134, v127, s[58:59]
.Lmb_nomask:
	v_max3_f32 v154, v96, v97, v98
	v_max3_f32 v154, v154, v99, v100
	v_max3_f32 v154, v154, v101, v102
	v_max3_f32 v154, v154, v103, v104
	v_max3_f32 v154, v154, v105, v106
	v_max3_f32 v154, v154, v107, v108
	v_max3_f32 v154, v154, v109, v110
	v_max_f32_e32 v154, v154, v111
	v_max3_f32 v155, v112, v113, v114
	v_max3_f32 v155, v155, v115, v116
	v_max3_f32 v155, v155, v117, v118
	v_max3_f32 v155, v155, v119, v120
	v_max3_f32 v155, v155, v121, v122
	v_max3_f32 v155, v155, v123, v124
	v_max3_f32 v155, v155, v125, v126
	v_max_f32_e32 v155, v155, v127
	ds_bpermute_b32 v157, v201, v154
	ds_bpermute_b32 v158, v201, v155
	s_waitcnt lgkmcnt(0)
	v_max_f32_e32 v154, v154, v157
	v_max_f32_e32 v155, v155, v158
	ds_bpermute_b32 v157, v202, v154
	ds_bpermute_b32 v158, v202, v155
	s_waitcnt lgkmcnt(0)
	v_max_f32_e32 v154, v154, v157
	v_max_f32_e32 v155, v155, v158
	v_cmp_ge_f32_e32 vcc, s72, v154
	s_cmp_eq_u64 vcc, exec
	s_cbranch_scc1 .Lmb_norescale_1
	v_max_f32_e32 v159, 0, v154
	v_cmp_gt_f32_e32 vcc, s74, v148
	v_add_f32_e32 v160, v146, v159
	v_add_f32_e32 v161, v148, v159
	s_nop 0
	v_cndmask_b32_e32 v160, v161, v160, vcc
	v_sub_f32_e32 v161, v148, v160
	v_exp_f32_e32 v161, v161
	v_mov_b32_e32 v148, v160
	v_mul_f32_e32 v150, v150, v161
	v_mul_f32_e32 v0, v0, v161
	v_mul_f32_e32 v1, v1, v161
	v_mul_f32_e32 v2, v2, v161
	v_mul_f32_e32 v3, v3, v161
	v_mul_f32_e32 v4, v4, v161
	v_mul_f32_e32 v5, v5, v161
	v_mul_f32_e32 v6, v6, v161
	v_mul_f32_e32 v7, v7, v161
	v_mul_f32_e32 v8, v8, v161
	v_mul_f32_e32 v9, v9, v161
	v_mul_f32_e32 v10, v10, v161
	v_mul_f32_e32 v11, v11, v161
	v_mul_f32_e32 v12, v12, v161
	v_mul_f32_e32 v13, v13, v161
	v_mul_f32_e32 v14, v14, v161
	v_mul_f32_e32 v15, v15, v161
	v_mul_f32_e32 v16, v16, v161
	v_mul_f32_e32 v17, v17, v161
	v_mul_f32_e32 v18, v18, v161
	v_mul_f32_e32 v19, v19, v161
	v_mul_f32_e32 v20, v20, v161
	v_mul_f32_e32 v21, v21, v161
	v_mul_f32_e32 v22, v22, v161
	v_mul_f32_e32 v23, v23, v161
	v_mul_f32_e32 v24, v24, v161
	v_mul_f32_e32 v25, v25, v161
	v_mul_f32_e32 v26, v26, v161
	v_mul_f32_e32 v27, v27, v161
	v_mul_f32_e32 v28, v28, v161
	v_mul_f32_e32 v29, v29, v161
	v_mul_f32_e32 v30, v30, v161
	v_mul_f32_e32 v31, v31, v161
	v_sub_f32_e32 v96, v96, v159
	v_sub_f32_e32 v97, v97, v159
	v_sub_f32_e32 v98, v98, v159
	v_sub_f32_e32 v99, v99, v159
	v_sub_f32_e32 v100, v100, v159
	v_sub_f32_e32 v101, v101, v159
	v_sub_f32_e32 v102, v102, v159
	v_sub_f32_e32 v103, v103, v159
	v_sub_f32_e32 v104, v104, v159
	v_sub_f32_e32 v105, v105, v159
	v_sub_f32_e32 v106, v106, v159
	v_sub_f32_e32 v107, v107, v159
	v_sub_f32_e32 v108, v108, v159
	v_sub_f32_e32 v109, v109, v159
	v_sub_f32_e32 v110, v110, v159
	v_sub_f32_e32 v111, v111, v159
.Lmb_norescale_1:
	v_cmp_ge_f32_e32 vcc, s72, v155
	s_cmp_eq_u64 vcc, exec
	s_cbranch_scc1 .Lmb_norescale_2
	v_max_f32_e32 v159, 0, v155
	v_cmp_gt_f32_e32 vcc, s74, v149
	v_add_f32_e32 v160, v147, v159
	v_add_f32_e32 v161, v149, v159
	s_nop 0
	v_cndmask_b32_e32 v160, v161, v160, vcc
	v_sub_f32_e32 v161, v149, v160
	v_exp_f32_e32 v161, v161
	v_mov_b32_e32 v149, v160
	v_mul_f32_e32 v151, v151, v161
	v_mul_f32_e32 v32, v32, v161
	v_mul_f32_e32 v33, v33, v161
	v_mul_f32_e32 v34, v34, v161
	v_mul_f32_e32 v35, v35, v161
	v_mul_f32_e32 v36, v36, v161
	v_mul_f32_e32 v37, v37, v161
	v_mul_f32_e32 v38, v38, v161
	v_mul_f32_e32 v39, v39, v161
	v_mul_f32_e32 v40, v40, v161
	v_mul_f32_e32 v41, v41, v161
	v_mul_f32_e32 v42, v42, v161
	v_mul_f32_e32 v43, v43, v161
	v_mul_f32_e32 v44, v44, v161
	v_mul_f32_e32 v45, v45, v161
	v_mul_f32_e32 v46, v46, v161
	v_mul_f32_e32 v47, v47, v161
	v_mul_f32_e32 v48, v48, v161
	v_mul_f32_e32 v49, v49, v161
	v_mul_f32_e32 v50, v50, v161
	v_mul_f32_e32 v51, v51, v161
	v_mul_f32_e32 v52, v52, v161
	v_mul_f32_e32 v53, v53, v161
	v_mul_f32_e32 v54, v54, v161
	v_mul_f32_e32 v55, v55, v161
	v_mul_f32_e32 v56, v56, v161
	v_mul_f32_e32 v57, v57, v161
	v_mul_f32_e32 v58, v58, v161
	v_mul_f32_e32 v59, v59, v161
	v_mul_f32_e32 v60, v60, v161
	v_mul_f32_e32 v61, v61, v161
	v_mul_f32_e32 v62, v62, v161
	v_mul_f32_e32 v63, v63, v161
	v_sub_f32_e32 v112, v112, v159
	v_sub_f32_e32 v113, v113, v159
	v_sub_f32_e32 v114, v114, v159
	v_sub_f32_e32 v115, v115, v159
	v_sub_f32_e32 v116, v116, v159
	v_sub_f32_e32 v117, v117, v159
	v_sub_f32_e32 v118, v118, v159
	v_sub_f32_e32 v119, v119, v159
	v_sub_f32_e32 v120, v120, v159
	v_sub_f32_e32 v121, v121, v159
	v_sub_f32_e32 v122, v122, v159
	v_sub_f32_e32 v123, v123, v159
	v_sub_f32_e32 v124, v124, v159
	v_sub_f32_e32 v125, v125, v159
	v_sub_f32_e32 v126, v126, v159
	v_sub_f32_e32 v127, v127, v159
.Lmb_norescale_2:
	v_exp_f32_e32 v96, v96
	v_exp_f32_e32 v97, v97
	v_mov_b32_e32 v159, v96
	v_exp_f32_e32 v98, v98
	v_add_f32_e32 v159, v159, v97
	v_exp_f32_e32 v99, v99
	v_add_f32_e32 v159, v159, v98
	v_exp_f32_e32 v100, v100
	v_add_f32_e32 v159, v159, v99
	v_exp_f32_e32 v101, v101
	v_add_f32_e32 v159, v159, v100
	v_exp_f32_e32 v102, v102
	v_add_f32_e32 v159, v159, v101
	v_exp_f32_e32 v103, v103
	v_add_f32_e32 v159, v159, v102
	v_exp_f32_e32 v104, v104
	v_add_f32_e32 v159, v159, v103
	v_exp_f32_e32 v105, v105
	v_add_f32_e32 v159, v159, v104
	v_exp_f32_e32 v106, v106
	v_add_f32_e32 v159, v159, v105
	v_exp_f32_e32 v107, v107
	v_add_f32_e32 v159, v159, v106
	v_exp_f32_e32 v108, v108
	v_add_f32_e32 v159, v159, v107
	v_exp_f32_e32 v109, v109
	v_add_f32_e32 v159, v159, v108
	v_exp_f32_e32 v110, v110
	v_add_f32_e32 v159, v159, v109
	v_exp_f32_e32 v111, v111
	v_add_f32_e32 v159, v159, v110
	s_nop 0
	v_add_f32_e32 v159, v159, v111
	v_add_f32_e32 v150, v150, v159
	v_cvt_pk_bf16_f32 v96, v96, v97
	v_cvt_pk_bf16_f32 v97, v98, v99
	v_cvt_pk_bf16_f32 v98, v100, v101
	v_cvt_pk_bf16_f32 v99, v102, v103
	v_cvt_pk_bf16_f32 v104, v104, v105
	v_cvt_pk_bf16_f32 v105, v106, v107
	v_cvt_pk_bf16_f32 v106, v108, v109
	v_cvt_pk_bf16_f32 v107, v110, v111
	v_exp_f32_e32 v112, v112
	v_exp_f32_e32 v113, v113
	v_mov_b32_e32 v159, v112
	v_exp_f32_e32 v114, v114
	v_add_f32_e32 v159, v159, v113
	v_exp_f32_e32 v115, v115
	v_add_f32_e32 v159, v159, v114
	v_exp_f32_e32 v116, v116
	v_add_f32_e32 v159, v159, v115
	v_exp_f32_e32 v117, v117
	v_add_f32_e32 v159, v159, v116
	v_exp_f32_e32 v118, v118
	v_add_f32_e32 v159, v159, v117
	v_exp_f32_e32 v119, v119
	v_add_f32_e32 v159, v159, v118
	v_exp_f32_e32 v120, v120
	v_add_f32_e32 v159, v159, v119
	v_exp_f32_e32 v121, v121
	v_add_f32_e32 v159, v159, v120
	v_exp_f32_e32 v122, v122
	v_add_f32_e32 v159, v159, v121
	v_exp_f32_e32 v123, v123
	v_add_f32_e32 v159, v159, v122
	v_exp_f32_e32 v124, v124
	v_add_f32_e32 v159, v159, v123
	v_exp_f32_e32 v125, v125
	v_add_f32_e32 v159, v159, v124
	v_exp_f32_e32 v126, v126
	v_add_f32_e32 v159, v159, v125
	v_exp_f32_e32 v127, v127
	v_add_f32_e32 v159, v159, v126
	s_nop 0
	v_add_f32_e32 v159, v159, v127
	v_add_f32_e32 v151, v151, v159
	v_cvt_pk_bf16_f32 v112, v112, v113
	v_cvt_pk_bf16_f32 v113, v114, v115
	v_cvt_pk_bf16_f32 v114, v116, v117
	v_cvt_pk_bf16_f32 v115, v118, v119
	v_cvt_pk_bf16_f32 v120, v120, v121
	v_cvt_pk_bf16_f32 v121, v122, v123
	v_cvt_pk_bf16_f32 v122, v124, v125
	v_cvt_pk_bf16_f32 v123, v126, v127
	ds_read_b64_tr_b16 v[248:249], v129 offset:192
	ds_read_b64_tr_b16 v[250:251], v129 offset:4800
	s_nop 1
	s_waitcnt lgkmcnt(12)
	v_mfma_f32_16x16x32_bf16 v[0:3], v[204:207], v[96:99], v[0:3]
	v_mfma_f32_16x16x32_bf16 v[32:35], v[204:207], v[112:115], v[32:35]
	ds_read_b64_tr_b16 v[252:253], v129 offset:224
	ds_read_b64_tr_b16 v[254:255], v129 offset:4832
	s_waitcnt lgkmcnt(12)
	v_mfma_f32_16x16x32_bf16 v[4:7], v[208:211], v[96:99], v[4:7]
	v_mfma_f32_16x16x32_bf16 v[36:39], v[208:211], v[112:115], v[36:39]
	ds_read_b64_tr_b16 v[204:205], v129 offset:9216
	ds_read_b64_tr_b16 v[206:207], v129 offset:13824
	s_waitcnt lgkmcnt(12)
	v_mfma_f32_16x16x32_bf16 v[8:11], v[212:215], v[96:99], v[8:11]
	v_mfma_f32_16x16x32_bf16 v[40:43], v[212:215], v[112:115], v[40:43]
	ds_read_b64_tr_b16 v[208:209], v129 offset:9248
	ds_read_b64_tr_b16 v[210:211], v129 offset:13856
	s_waitcnt lgkmcnt(12)
	v_mfma_f32_16x16x32_bf16 v[12:15], v[216:219], v[96:99], v[12:15]
	v_mfma_f32_16x16x32_bf16 v[44:47], v[216:219], v[112:115], v[44:47]
	ds_read_b64_tr_b16 v[212:213], v129 offset:9280
	ds_read_b64_tr_b16 v[214:215], v129 offset:13888
	s_waitcnt lgkmcnt(12)
	v_mfma_f32_16x16x32_bf16 v[16:19], v[240:243], v[96:99], v[16:19]
	v_mfma_f32_16x16x32_bf16 v[48:51], v[240:243], v[112:115], v[48:51]
	ds_read_b64_tr_b16 v[216:217], v129 offset:9312
	ds_read_b64_tr_b16 v[218:219], v129 offset:13920
	s_waitcnt lgkmcnt(12)
	v_mfma_f32_16x16x32_bf16 v[20:23], v[244:247], v[96:99], v[20:23]
	v_mfma_f32_16x16x32_bf16 v[52:55], v[244:247], v[112:115], v[52:55]
	ds_read_b64_tr_b16 v[240:241], v129 offset:9344
	ds_read_b64_tr_b16 v[242:243], v129 offset:13952
	s_waitcnt lgkmcnt(12)
	v_mfma_f32_16x16x32_bf16 v[24:27], v[248:251], v[96:99], v[24:27]
	v_mfma_f32_16x16x32_bf16 v[56:59], v[248:251], v[112:115], v[56:59]
	ds_read_b64_tr_b16 v[244:245], v129 offset:9376
	ds_read_b64_tr_b16 v[246:247], v129 offset:13984
	s_waitcnt lgkmcnt(12)
	v_mfma_f32_16x16x32_bf16 v[28:31], v[252:255], v[96:99], v[28:31]
	v_mfma_f32_16x16x32_bf16 v[60:63], v[252:255], v[112:115], v[60:63]
	ds_read_b64_tr_b16 v[248:249], v129 offset:9408
	ds_read_b64_tr_b16 v[250:251], v129 offset:14016
	s_waitcnt lgkmcnt(12)
	v_mfma_f32_16x16x32_bf16 v[0:3], v[204:207], v[104:107], v[0:3]
	v_mfma_f32_16x16x32_bf16 v[32:35], v[204:207], v[120:123], v[32:35]
	ds_read_b64_tr_b16 v[252:253], v129 offset:9440
	ds_read_b64_tr_b16 v[254:255], v129 offset:14048
	s_waitcnt lgkmcnt(12)
	v_mfma_f32_16x16x32_bf16 v[4:7], v[208:211], v[104:107], v[4:7]
	v_mfma_f32_16x16x32_bf16 v[36:39], v[208:211], v[120:123], v[36:39]
	s_waitcnt lgkmcnt(10)
	v_mfma_f32_16x16x32_bf16 v[8:11], v[212:215], v[104:107], v[8:11]
	v_mfma_f32_16x16x32_bf16 v[40:43], v[212:215], v[120:123], v[40:43]
	s_waitcnt lgkmcnt(8)
	v_mfma_f32_16x16x32_bf16 v[12:15], v[216:219], v[104:107], v[12:15]
	v_mfma_f32_16x16x32_bf16 v[44:47], v[216:219], v[120:123], v[44:47]
	s_waitcnt lgkmcnt(6)
	v_mfma_f32_16x16x32_bf16 v[16:19], v[240:243], v[104:107], v[16:19]
	v_mfma_f32_16x16x32_bf16 v[48:51], v[240:243], v[120:123], v[48:51]
	s_waitcnt lgkmcnt(4)
	v_mfma_f32_16x16x32_bf16 v[20:23], v[244:247], v[104:107], v[20:23]
	v_mfma_f32_16x16x32_bf16 v[52:55], v[244:247], v[120:123], v[52:55]
	s_waitcnt lgkmcnt(2)
	v_mfma_f32_16x16x32_bf16 v[24:27], v[248:251], v[104:107], v[24:27]
	v_mfma_f32_16x16x32_bf16 v[56:59], v[248:251], v[120:123], v[56:59]
	s_waitcnt lgkmcnt(0)
	v_mfma_f32_16x16x32_bf16 v[28:31], v[252:255], v[104:107], v[28:31]
	v_mfma_f32_16x16x32_bf16 v[60:63], v[252:255], v[120:123], v[60:63]
.Lmb_iter_end:
	v_xor_b32_e32 v128, 65536, v128
	v_xor_b32_e32 v129, 65536, v129
	v_xor_b32_e32 v130, 65536, v130
	v_xor_b32_e32 v131, 65536, v131
	s_add_u32 s17, s17, 1
	s_waitcnt lgkmcnt(0)
	s_barrier
	s_cmp_lt_u32 s17, s16
	s_cbranch_scc1 .Lmb_loop
	s_nop 7
	ds_bpermute_b32 v157, v201, v150
	ds_bpermute_b32 v158, v201, v151
	s_waitcnt lgkmcnt(0)
	v_add_f32_e32 v150, v150, v157
	v_add_f32_e32 v151, v151, v158
	ds_bpermute_b32 v157, v202, v150
	ds_bpermute_b32 v158, v202, v151
	s_waitcnt lgkmcnt(0)
	v_add_f32_e32 v150, v150, v157
	v_add_f32_e32 v151, v151, v158
	v_div_scale_f32 v161, s[80:81], v150, v150, 1.0
	v_rcp_f32_e32 v162, v161
	v_div_scale_f32 v163, vcc, 1.0, v150, 1.0
	v_fma_f32 v192, -v161, v162, 1.0
	v_fmac_f32_e32 v162, v192, v162
	v_mul_f32_e32 v192, v163, v162
	v_fma_f32 v193, -v161, v192, v163
	v_fmac_f32_e32 v192, v193, v162
	v_fma_f32 v161, -v161, v192, v163
	v_div_fmas_f32 v161, v161, v162, v192
	v_div_fixup_f32 v159, v161, v150, 1.0
	v_div_scale_f32 v161, s[80:81], v151, v151, 1.0
	v_rcp_f32_e32 v162, v161
	v_div_scale_f32 v163, vcc, 1.0, v151, 1.0
	v_fma_f32 v192, -v161, v162, 1.0
	v_fmac_f32_e32 v162, v192, v162
	v_mul_f32_e32 v192, v163, v162
	v_fma_f32 v193, -v161, v192, v163
	v_fmac_f32_e32 v192, v193, v162
	v_fma_f32 v161, -v161, v192, v163
	v_div_fmas_f32 v161, v161, v162, v192
	v_div_fixup_f32 v160, v161, v151, 1.0
	v_and_b32_e32 v139, 15, v165
	s_lshl_b32 s25, s7, 5
	v_add_u32_e32 v139, s25, v139
	v_lshrrev_b32_e32 v140, 4, v165
	v_lshlrev_b32_e32 v140, 3, v140
	v_lshl_add_u32 v141, v139, 14, v140
	v_lshl_add_u32 v142, v139, 12, v140
	s_add_u32 s22, s18, 6144
	s_addc_u32 s23, s19, 0
	global_load_dwordx2 v[96:97], v141, s[22:23] offset:0
	global_load_dwordx2 v[98:99], v141, s[22:23] offset:32
	global_load_dwordx2 v[100:101], v141, s[22:23] offset:64
	global_load_dwordx2 v[102:103], v141, s[22:23] offset:96
	global_load_dwordx2 v[104:105], v141, s[22:23] offset:128
	global_load_dwordx2 v[106:107], v141, s[22:23] offset:160
	global_load_dwordx2 v[108:109], v141, s[22:23] offset:192
	global_load_dwordx2 v[110:111], v141, s[22:23] offset:224
	s_add_u32 s22, s18, 268288
	s_addc_u32 s23, s19, 0
	global_load_dwordx2 v[112:113], v141, s[22:23] offset:0
	global_load_dwordx2 v[114:115], v141, s[22:23] offset:32
	global_load_dwordx2 v[116:117], v141, s[22:23] offset:64
	global_load_dwordx2 v[118:119], v141, s[22:23] offset:96
	global_load_dwordx2 v[120:121], v141, s[22:23] offset:128
	global_load_dwordx2 v[122:123], v141, s[22:23] offset:160
	global_load_dwordx2 v[124:125], v141, s[22:23] offset:192
	global_load_dwordx2 v[126:127], v141, s[22:23] offset:224
	s_lshl_b32 s25, s15, 20
	s_add_u32 s20, s10, s25
	s_addc_u32 s21, s11, 0
	s_waitcnt vmcnt(15)
	v_mul_f32_e32 v161, v0, v159
	v_mul_f32_e32 v162, v1, v159
	v_mul_f32_e32 v163, v2, v159
	v_mul_f32_e32 v192, v3, v159
	v_lshlrev_b32_e32 v193, 16, v96
	v_and_b32_e32 v195, 0xffff0000, v96
	v_mul_f32_e32 v161, v161, v193
	v_mul_f32_e32 v162, v162, v195
	v_lshlrev_b32_e32 v193, 16, v97
	v_and_b32_e32 v195, 0xffff0000, v97
	v_mul_f32_e32 v163, v163, v193
	v_mul_f32_e32 v192, v192, v195
	v_cvt_pk_bf16_f32 v96, v161, v162
	v_cvt_pk_bf16_f32 v97, v163, v192
	global_store_dwordx2 v142, v[96:97], s[20:21] offset:0
	s_waitcnt vmcnt(15)
	v_mul_f32_e32 v161, v4, v159
	v_mul_f32_e32 v162, v5, v159
	v_mul_f32_e32 v163, v6, v159
	v_mul_f32_e32 v192, v7, v159
	v_lshlrev_b32_e32 v193, 16, v98
	v_and_b32_e32 v195, 0xffff0000, v98
	v_mul_f32_e32 v161, v161, v193
	v_mul_f32_e32 v162, v162, v195
	v_lshlrev_b32_e32 v193, 16, v99
	v_and_b32_e32 v195, 0xffff0000, v99
	v_mul_f32_e32 v163, v163, v193
	v_mul_f32_e32 v192, v192, v195
	v_cvt_pk_bf16_f32 v98, v161, v162
	v_cvt_pk_bf16_f32 v99, v163, v192
	global_store_dwordx2 v142, v[98:99], s[20:21] offset:32
	s_waitcnt vmcnt(15)
	v_mul_f32_e32 v161, v8, v159
	v_mul_f32_e32 v162, v9, v159
	v_mul_f32_e32 v163, v10, v159
	v_mul_f32_e32 v192, v11, v159
	v_lshlrev_b32_e32 v193, 16, v100
	v_and_b32_e32 v195, 0xffff0000, v100
	v_mul_f32_e32 v161, v161, v193
	v_mul_f32_e32 v162, v162, v195
	v_lshlrev_b32_e32 v193, 16, v101
	v_and_b32_e32 v195, 0xffff0000, v101
	v_mul_f32_e32 v163, v163, v193
	v_mul_f32_e32 v192, v192, v195
	v_cvt_pk_bf16_f32 v100, v161, v162
	v_cvt_pk_bf16_f32 v101, v163, v192
	global_store_dwordx2 v142, v[100:101], s[20:21] offset:64
	s_waitcnt vmcnt(15)
	v_mul_f32_e32 v161, v12, v159
	v_mul_f32_e32 v162, v13, v159
	v_mul_f32_e32 v163, v14, v159
	v_mul_f32_e32 v192, v15, v159
	v_lshlrev_b32_e32 v193, 16, v102
	v_and_b32_e32 v195, 0xffff0000, v102
	v_mul_f32_e32 v161, v161, v193
	v_mul_f32_e32 v162, v162, v195
	v_lshlrev_b32_e32 v193, 16, v103
	v_and_b32_e32 v195, 0xffff0000, v103
	v_mul_f32_e32 v163, v163, v193
	v_mul_f32_e32 v192, v192, v195
	v_cvt_pk_bf16_f32 v102, v161, v162
	v_cvt_pk_bf16_f32 v103, v163, v192
	global_store_dwordx2 v142, v[102:103], s[20:21] offset:96
	s_waitcnt vmcnt(15)
	v_mul_f32_e32 v161, v16, v159
	v_mul_f32_e32 v162, v17, v159
	v_mul_f32_e32 v163, v18, v159
	v_mul_f32_e32 v192, v19, v159
	v_lshlrev_b32_e32 v193, 16, v104
	v_and_b32_e32 v195, 0xffff0000, v104
	v_mul_f32_e32 v161, v161, v193
	v_mul_f32_e32 v162, v162, v195
	v_lshlrev_b32_e32 v193, 16, v105
	v_and_b32_e32 v195, 0xffff0000, v105
	v_mul_f32_e32 v163, v163, v193
	v_mul_f32_e32 v192, v192, v195
	v_cvt_pk_bf16_f32 v104, v161, v162
	v_cvt_pk_bf16_f32 v105, v163, v192
	global_store_dwordx2 v142, v[104:105], s[20:21] offset:128
	s_waitcnt vmcnt(15)
	v_mul_f32_e32 v161, v20, v159
	v_mul_f32_e32 v162, v21, v159
	v_mul_f32_e32 v163, v22, v159
	v_mul_f32_e32 v192, v23, v159
	v_lshlrev_b32_e32 v193, 16, v106
	v_and_b32_e32 v195, 0xffff0000, v106
	v_mul_f32_e32 v161, v161, v193
	v_mul_f32_e32 v162, v162, v195
	v_lshlrev_b32_e32 v193, 16, v107
	v_and_b32_e32 v195, 0xffff0000, v107
	v_mul_f32_e32 v163, v163, v193
	v_mul_f32_e32 v192, v192, v195
	v_cvt_pk_bf16_f32 v106, v161, v162
	v_cvt_pk_bf16_f32 v107, v163, v192
	global_store_dwordx2 v142, v[106:107], s[20:21] offset:160
	s_waitcnt vmcnt(15)
	v_mul_f32_e32 v161, v24, v159
	v_mul_f32_e32 v162, v25, v159
	v_mul_f32_e32 v163, v26, v159
	v_mul_f32_e32 v192, v27, v159
	v_lshlrev_b32_e32 v193, 16, v108
	v_and_b32_e32 v195, 0xffff0000, v108
	v_mul_f32_e32 v161, v161, v193
	v_mul_f32_e32 v162, v162, v195
	v_lshlrev_b32_e32 v193, 16, v109
	v_and_b32_e32 v195, 0xffff0000, v109
	v_mul_f32_e32 v163, v163, v193
	v_mul_f32_e32 v192, v192, v195
	v_cvt_pk_bf16_f32 v108, v161, v162
	v_cvt_pk_bf16_f32 v109, v163, v192
	global_store_dwordx2 v142, v[108:109], s[20:21] offset:192
	s_waitcnt vmcnt(15)
	v_mul_f32_e32 v161, v28, v159
	v_mul_f32_e32 v162, v29, v159
	v_mul_f32_e32 v163, v30, v159
	v_mul_f32_e32 v192, v31, v159
	v_lshlrev_b32_e32 v193, 16, v110
	v_and_b32_e32 v195, 0xffff0000, v110
	v_mul_f32_e32 v161, v161, v193
	v_mul_f32_e32 v162, v162, v195
	v_lshlrev_b32_e32 v193, 16, v111
	v_and_b32_e32 v195, 0xffff0000, v111
	v_mul_f32_e32 v163, v163, v193
	v_mul_f32_e32 v192, v192, v195
	v_cvt_pk_bf16_f32 v110, v161, v162
	v_cvt_pk_bf16_f32 v111, v163, v192
	global_store_dwordx2 v142, v[110:111], s[20:21] offset:224
	s_add_u32 s20, s20, 0x10000
	s_addc_u32 s21, s21, 0
	s_waitcnt vmcnt(15)
	v_mul_f32_e32 v161, v32, v160
	v_mul_f32_e32 v162, v33, v160
	v_mul_f32_e32 v163, v34, v160
	v_mul_f32_e32 v192, v35, v160
	v_lshlrev_b32_e32 v193, 16, v112
	v_and_b32_e32 v195, 0xffff0000, v112
	v_mul_f32_e32 v161, v161, v193
	v_mul_f32_e32 v162, v162, v195
	v_lshlrev_b32_e32 v193, 16, v113
	v_and_b32_e32 v195, 0xffff0000, v113
	v_mul_f32_e32 v163, v163, v193
	v_mul_f32_e32 v192, v192, v195
	v_cvt_pk_bf16_f32 v112, v161, v162
	v_cvt_pk_bf16_f32 v113, v163, v192
	global_store_dwordx2 v142, v[112:113], s[20:21] offset:0
	s_waitcnt vmcnt(15)
	v_mul_f32_e32 v161, v36, v160
	v_mul_f32_e32 v162, v37, v160
	v_mul_f32_e32 v163, v38, v160
	v_mul_f32_e32 v192, v39, v160
	v_lshlrev_b32_e32 v193, 16, v114
	v_and_b32_e32 v195, 0xffff0000, v114
	v_mul_f32_e32 v161, v161, v193
	v_mul_f32_e32 v162, v162, v195
	v_lshlrev_b32_e32 v193, 16, v115
	v_and_b32_e32 v195, 0xffff0000, v115
	v_mul_f32_e32 v163, v163, v193
	v_mul_f32_e32 v192, v192, v195
	v_cvt_pk_bf16_f32 v114, v161, v162
	v_cvt_pk_bf16_f32 v115, v163, v192
	global_store_dwordx2 v142, v[114:115], s[20:21] offset:32
	s_waitcnt vmcnt(15)
	v_mul_f32_e32 v161, v40, v160
	v_mul_f32_e32 v162, v41, v160
	v_mul_f32_e32 v163, v42, v160
	v_mul_f32_e32 v192, v43, v160
	v_lshlrev_b32_e32 v193, 16, v116
	v_and_b32_e32 v195, 0xffff0000, v116
	v_mul_f32_e32 v161, v161, v193
	v_mul_f32_e32 v162, v162, v195
	v_lshlrev_b32_e32 v193, 16, v117
	v_and_b32_e32 v195, 0xffff0000, v117
	v_mul_f32_e32 v163, v163, v193
	v_mul_f32_e32 v192, v192, v195
	v_cvt_pk_bf16_f32 v116, v161, v162
	v_cvt_pk_bf16_f32 v117, v163, v192
	global_store_dwordx2 v142, v[116:117], s[20:21] offset:64
	s_waitcnt vmcnt(15)
	v_mul_f32_e32 v161, v44, v160
	v_mul_f32_e32 v162, v45, v160
	v_mul_f32_e32 v163, v46, v160
	v_mul_f32_e32 v192, v47, v160
	v_lshlrev_b32_e32 v193, 16, v118
	v_and_b32_e32 v195, 0xffff0000, v118
	v_mul_f32_e32 v161, v161, v193
	v_mul_f32_e32 v162, v162, v195
	v_lshlrev_b32_e32 v193, 16, v119
	v_and_b32_e32 v195, 0xffff0000, v119
	v_mul_f32_e32 v163, v163, v193
	v_mul_f32_e32 v192, v192, v195
	v_cvt_pk_bf16_f32 v118, v161, v162
	v_cvt_pk_bf16_f32 v119, v163, v192
	global_store_dwordx2 v142, v[118:119], s[20:21] offset:96
	s_waitcnt vmcnt(15)
	v_mul_f32_e32 v161, v48, v160
	v_mul_f32_e32 v162, v49, v160
	v_mul_f32_e32 v163, v50, v160
	v_mul_f32_e32 v192, v51, v160
	v_lshlrev_b32_e32 v193, 16, v120
	v_and_b32_e32 v195, 0xffff0000, v120
	v_mul_f32_e32 v161, v161, v193
	v_mul_f32_e32 v162, v162, v195
	v_lshlrev_b32_e32 v193, 16, v121
	v_and_b32_e32 v195, 0xffff0000, v121
	v_mul_f32_e32 v163, v163, v193
	v_mul_f32_e32 v192, v192, v195
	v_cvt_pk_bf16_f32 v120, v161, v162
	v_cvt_pk_bf16_f32 v121, v163, v192
	global_store_dwordx2 v142, v[120:121], s[20:21] offset:128
	s_waitcnt vmcnt(15)
	v_mul_f32_e32 v161, v52, v160
	v_mul_f32_e32 v162, v53, v160
	v_mul_f32_e32 v163, v54, v160
	v_mul_f32_e32 v192, v55, v160
	v_lshlrev_b32_e32 v193, 16, v122
	v_and_b32_e32 v195, 0xffff0000, v122
	v_mul_f32_e32 v161, v161, v193
	v_mul_f32_e32 v162, v162, v195
	v_lshlrev_b32_e32 v193, 16, v123
	v_and_b32_e32 v195, 0xffff0000, v123
	v_mul_f32_e32 v163, v163, v193
	v_mul_f32_e32 v192, v192, v195
	v_cvt_pk_bf16_f32 v122, v161, v162
	v_cvt_pk_bf16_f32 v123, v163, v192
	global_store_dwordx2 v142, v[122:123], s[20:21] offset:160
	s_waitcnt vmcnt(15)
	v_mul_f32_e32 v161, v56, v160
	v_mul_f32_e32 v162, v57, v160
	v_mul_f32_e32 v163, v58, v160
	v_mul_f32_e32 v192, v59, v160
	v_lshlrev_b32_e32 v193, 16, v124
	v_and_b32_e32 v195, 0xffff0000, v124
	v_mul_f32_e32 v161, v161, v193
	v_mul_f32_e32 v162, v162, v195
	v_lshlrev_b32_e32 v193, 16, v125
	v_and_b32_e32 v195, 0xffff0000, v125
	v_mul_f32_e32 v163, v163, v193
	v_mul_f32_e32 v192, v192, v195
	v_cvt_pk_bf16_f32 v124, v161, v162
	v_cvt_pk_bf16_f32 v125, v163, v192
	global_store_dwordx2 v142, v[124:125], s[20:21] offset:192
	s_waitcnt vmcnt(15)
	v_mul_f32_e32 v161, v60, v160
	v_mul_f32_e32 v162, v61, v160
	v_mul_f32_e32 v163, v62, v160
	v_mul_f32_e32 v192, v63, v160
	v_lshlrev_b32_e32 v193, 16, v126
	v_and_b32_e32 v195, 0xffff0000, v126
	v_mul_f32_e32 v161, v161, v193
	v_mul_f32_e32 v162, v162, v195
	v_lshlrev_b32_e32 v193, 16, v127
	v_and_b32_e32 v195, 0xffff0000, v127
	v_mul_f32_e32 v163, v163, v193
	v_mul_f32_e32 v192, v192, v195
	v_cvt_pk_bf16_f32 v126, v161, v162
	v_cvt_pk_bf16_f32 v127, v163, v192
	global_store_dwordx2 v142, v[126:127], s[20:21] offset:224
	s_add_u32 s14, s14, 1
	s_cmp_lt_u32 s14, 2
	s_cbranch_scc1 .Lmb_task
	v_cmp_gt_u32_e32 vcc, 64, v198
	s_nop 3
	s_and_saveexec_b64 s[2:3], vcc
	v_readlane_b32 s8, v236, 22
	v_readlane_b32 s22, v236, 36
	v_readlane_b32 s23, v236, 37
	v_readlane_b32 s14, v236, 28
	v_readlane_b32 s15, v236, 29
	v_readlane_b32 s20, v236, 34
	v_readlane_b32 s21, v236, 35
	s_mov_b64 s[82:83], s[22:23]
	s_xor_b64 s[2:3], exec, s[2:3]
	s_mov_b64 s[80:81], s[20:21]
	s_mov_b64 s[74:75], s[14:15]
	v_readlane_b32 s9, v236, 23
	v_readlane_b32 s10, v236, 24
	v_readlane_b32 s11, v236, 25
	v_readlane_b32 s12, v236, 26
	v_readlane_b32 s13, v236, 27
	v_readlane_b32 s16, v236, 30
	v_readlane_b32 s17, v236, 31
	v_readlane_b32 s18, v236, 32
	v_readlane_b32 s19, v236, 33
	s_cbranch_execz .LBB0_667
	s_mov_b64 s[4:5], exec
	v_readlane_b32 s6, v236, 19
	v_readlane_b32 s7, v236, 20
	s_and_b64 s[6:7], s[4:5], s[6:7]
	s_mov_b64 exec, s[6:7]
	s_cbranch_execz .LBB0_666
	s_lshl_b32 s6, s0, 1
	s_or_b32 s7, s6, 1
	s_cmp_lt_u32 s0, 4
	s_cselect_b32 s8, s6, s0
	s_cselect_b32 s0, s7, s0
	s_and_b32 s12, s34, 0xffffff8
	s_lshl_b64 s[6:7], s[42:43], 2
	s_add_u32 s6, s80, s6
	s_addc_u32 s7, s81, s7
	s_add_i32 s8, s12, s8
	s_lshl_b32 s10, s8, 6
	s_mov_b32 s11, 0
	s_lshl_b64 s[8:9], s[10:11], 2
	s_add_u32 s8, s80, s8
	s_addc_u32 s9, s81, s9
	s_add_i32 s0, s0, s12
	s_lshl_b32 s10, s0, 6
	s_lshl_b64 s[10:11], s[10:11], 2
	s_add_u32 s10, s80, s10
	s_addc_u32 s11, s81, s11
	s_mov_b32 s0, 0x1000000
	v_mov_b32_e32 v0, 0
	s_branch .LBB0_648

	.amdhsa_kernel _Z8fwd_mega6Params
		.amdhsa_group_segment_fixed_size 0
		.amdhsa_private_segment_fixed_size 0
		.amdhsa_kernarg_size 520
		.amdhsa_user_sgpr_count 2
		.amdhsa_user_sgpr_dispatch_ptr 0
		.amdhsa_user_sgpr_queue_ptr 0
		.amdhsa_user_sgpr_kernarg_segment_ptr 1
		.amdhsa_user_sgpr_dispatch_id 0
		.amdhsa_user_sgpr_kernarg_preload_length 0
		.amdhsa_user_sgpr_kernarg_preload_offset 0
		.amdhsa_user_sgpr_private_segment_size 0
		.amdhsa_uses_dynamic_stack 0
		.amdhsa_enable_private_segment 0
		.amdhsa_system_sgpr_workgroup_id_x 1
		.amdhsa_system_sgpr_workgroup_id_y 0
		.amdhsa_system_sgpr_workgroup_id_z 0
		.amdhsa_system_sgpr_workgroup_info 0
		.amdhsa_system_vgpr_workitem_id 2
		.amdhsa_next_free_vgpr 256
		.amdhsa_next_free_sgpr 98
		.amdhsa_accum_offset 256
		.amdhsa_reserve_vcc 1
		.amdhsa_float_round_mode_32 0
		.amdhsa_float_round_mode_16_64 0
		.amdhsa_float_denorm_mode_32 3
		.amdhsa_float_denorm_mode_16_64 3
		.amdhsa_dx10_clamp 1
		.amdhsa_ieee_mode 1
		.amdhsa_fp16_overflow 0
		.amdhsa_tg_split 0
		.amdhsa_exception_fp_ieee_invalid_op 0
		.amdhsa_exception_fp_denorm_src 0
		.amdhsa_exception_fp_ieee_div_zero 0
		.amdhsa_exception_fp_ieee_overflow 0
		.amdhsa_exception_fp_ieee_underflow 0
		.amdhsa_exception_fp_ieee_inexact 0
		.amdhsa_exception_int_div_zero 0
	.end_amdhsa_kernel

amdhsa.kernels:
  - .agpr_count:     0
    .args:
      - .offset:         0
        .size:           264
        .value_kind:     by_value
      - .offset:         264
        .size:           4
        .value_kind:     hidden_block_count_x
      - .offset:         268
        .size:           4
        .value_kind:     hidden_block_count_y
      - .offset:         272
        .size:           4
        .value_kind:     hidden_block_count_z
      - .offset:         276
        .size:           2
        .value_kind:     hidden_group_size_x
      - .offset:         278
        .size:           2
        .value_kind:     hidden_group_size_y
      - .offset:         280
        .size:           2
        .value_kind:     hidden_group_size_z
      - .offset:         282
        .size:           2
        .value_kind:     hidden_remainder_x
      - .offset:         284
        .size:           2
        .value_kind:     hidden_remainder_y
      - .offset:         286
        .size:           2
        .value_kind:     hidden_remainder_z
      - .offset:         304
        .size:           8
        .value_kind:     hidden_global_offset_x
      - .offset:         312
        .size:           8
        .value_kind:     hidden_global_offset_y
      - .offset:         320
        .size:           8
        .value_kind:     hidden_global_offset_z
      - .offset:         328
        .size:           2
        .value_kind:     hidden_grid_dims
      - .offset:         352
        .size:           8
        .value_kind:     hidden_multigrid_sync_arg
      - .offset:         384
        .size:           4
        .value_kind:     hidden_dynamic_lds_size
    .group_segment_fixed_size: 0
    .kernarg_segment_align: 8
    .kernarg_segment_size: 520
    .language:       OpenCL C
    .language_version:
      - 2
      - 0
    .max_flat_workgroup_size: 512
    .name:           _Z8fwd_mega6Params
    .private_segment_fixed_size: 0
    .sgpr_count:     104
    .sgpr_spill_count: 41
    .symbol:         _Z8fwd_mega6Params.kd
    .uniform_work_group_size: 1
    .uses_dynamic_stack: false
    .vgpr_count:     256
    .vgpr_spill_count: 0
    .wavefront_size: 64
